# K-loop LDS-DMA loads use SGPR-base + 32-bit VGPR-offset addressing (removes 12-16 64-bit VALU adds per K-iteration from the load segments; +128 K-tile step via inst offset with m0 compensated), on top
# speedup vs baseline: 1.0053x; 1.0015x over previous
; #define PG8_STAGE(bufoff, gbase, voff) do { _Pragma("unroll") for (int _i = 0; _i < 2; ++_i) \
;         __builtin_amdgcn_global_load_lds((const unsigned*)((const char*)(gbase) + (voff)[_i]), (PG8_LAS unsigned*)(lds + (bufoff) + ldsw + _i * 8192), 16, 0, 0); } while (0)
; #define PG8_LDA(dst, b, h) do { _Pragma("unroll") for (int m = 0; m < 4; ++m) _Pragma("unroll") for (int k = 0; k < 2; ++k) dst[m][k] = *(const PG8_LAS bf16x8*)(lds + PG8_SA(b, h) + aoff + m * 2048 + k * 1024); } while (0)
; #define PG8_LDB(dst, b, h) do { _Pragma("unroll") for (int n = 0; n < 2; ++n) _Pragma("unroll") for (int k = 0; k < 2; ++k) dst[n][k] = *(const PG8_LAS bf16x8*)(lds + PG8_SB(b, h) + boff + n * 2048 + k * 1024); } while (0)
; #define PG8_MMA(ai, bj, At, Bt) do { __builtin_amdgcn_s_setprio(1); _Pragma("unroll") for (int m = 0; m < 4; ++m) _Pragma("unroll") for (int n = 0; n < 2; ++n) _Pragma("unroll") for (int k = 0; k < 2; ++k) \
;         acc[ai][bj][m][n] = __builtin_amdgcn_mfma_f32_16x16x32_bf16(Bt[n][k], At[m][k], acc[ai][bj][m][n], 0, 0, 0); __builtin_amdgcn_s_setprio(0); } while (0)
; #define PG8_WAIT_V(n) asm volatile("s_waitcnt vmcnt(" #n ")" ::: "memory")
; #define PG8_WAIT_L(n) asm volatile("s_waitcnt lgkmcnt(" #n ")" ::: "memory")
; #define PG8_BAR __builtin_amdgcn_s_barrier()
; #define PG8_SCHED __builtin_amdgcn_sched_barrier(0)
; template <class Epi, class Sched, bool ALIGN_EPI = false, bool SP2 = false>
; __device__ __forceinline__ void gemm_phase(PG8_LAS unsigned char* lds, const Gemm g, const Sched& S, const Epi& E) {
;     ...
;             PG8_LDB(B0, 0, 0); PG8_LDB(B1, 0, 1); PG8_SCHED; PG8_LDA(At, 0, 0); PG8_STAGE(PG8_SA(1, 1), a1 + hstepA, voffA);
;             PG8_WAIT_V(8); PG8_WAIT_L(0); PG8_BAR; PG8_MMA(0, 0, At, B0); PG8_MMA(0, 1, At, B1); PG8_BAR; PG8_SCHED;
;             PG8_LDA(At, 0, 1); PG8_STAGE(PG8_SB(0, 0), b2, voffB); PG8_STAGE(PG8_SB(0, 1), b2 + hstepB, voffB); PG8_STAGE(PG8_SA(0, 0), a2, voffA);
;             PG8_WAIT_V(8); PG8_WAIT_L(0); PG8_BAR; PG8_MMA(1, 0, At, B0); PG8_MMA(1, 1, At, B1); PG8_BAR; PG8_SCHED;
.LBB0_634:
	s_add_u32 s2, s0, 0xfffc0080
	s_addc_u32 s3, s1, -1
	s_add_i32 s30, 0, 0x10000
	s_cmp_eq_u32 s95, 12
	s_cselect_b32 s85, s17, s3
	s_cselect_b32 s84, s78, s2
	s_cselect_b32 s7, s15, s94
	s_cselect_b32 s6, s87, s93
	s_add_i32 s31, 0, 0x14000
	v_add_u32_e32 v140, s30, v230
	v_add_u32_e32 v156, s31, v230
	ds_read_b128 v[112:115], v140
	ds_read_b128 v[120:123], v140 offset:1024
	ds_read_b128 v[128:131], v140 offset:2048
	ds_read_b128 v[140:143], v140 offset:3072
	ds_read_b128 v[144:147], v156
	ds_read_b128 v[148:151], v156 offset:1024
	ds_read_b128 v[152:155], v156 offset:2048
	ds_read_b128 v[156:159], v156 offset:3072
	s_add_i32 m0, s20, 0xc000
	ds_read_b128 v[160:163], v231
	ds_read_b128 v[164:167], v231 offset:1024
	ds_read_b128 v[168:171], v231 offset:2048
	ds_read_b128 v[172:175], v231 offset:3072
	ds_read_b128 v[186:189], v231 offset:4096
	ds_read_b128 v[198:201], v231 offset:5120
	ds_read_b128 v[202:205], v231 offset:6144
	ds_read_b128 v[206:209], v231 offset:7168
	global_load_lds_dwordx4 v184, s[0:1]
	s_add_i32 m0, s20, 0xe000
	s_nop 0
	global_load_lds_dwordx4 v182, s[0:1]
	s_waitcnt vmcnt(8)
	s_waitcnt lgkmcnt(0)
	s_barrier
	s_setprio 1
	s_waitcnt lgkmcnt(0)
	v_mfma_f32_16x16x32_bf16 v[136:139], v[112:115], v[160:163], v[136:139]
	v_mfma_f32_16x16x32_bf16 v[132:135], v[128:131], v[160:163], v[132:135]
	v_mfma_f32_16x16x32_bf16 v[108:111], v[112:115], v[168:171], v[108:111]
	v_mfma_f32_16x16x32_bf16 v[104:107], v[128:131], v[168:171], v[104:107]
	v_mfma_f32_16x16x32_bf16 v[92:95], v[112:115], v[186:189], v[92:95]
	v_mfma_f32_16x16x32_bf16 v[88:91], v[128:131], v[186:189], v[88:91]
	v_mfma_f32_16x16x32_bf16 v[76:79], v[112:115], v[202:205], v[76:79]
	v_mfma_f32_16x16x32_bf16 v[72:75], v[128:131], v[202:205], v[72:75]
	v_mfma_f32_16x16x32_bf16 v[136:139], v[120:123], v[164:167], v[136:139]
	v_mfma_f32_16x16x32_bf16 v[132:135], v[140:143], v[164:167], v[132:135]
	v_mfma_f32_16x16x32_bf16 v[108:111], v[120:123], v[172:175], v[108:111]
	v_mfma_f32_16x16x32_bf16 v[104:107], v[140:143], v[172:175], v[104:107]
	v_mfma_f32_16x16x32_bf16 v[92:95], v[120:123], v[198:201], v[92:95]
	v_mfma_f32_16x16x32_bf16 v[88:91], v[140:143], v[198:201], v[88:91]
	v_mfma_f32_16x16x32_bf16 v[76:79], v[120:123], v[206:209], v[76:79]
	v_mfma_f32_16x16x32_bf16 v[72:75], v[140:143], v[206:209], v[72:75]
	s_setprio 0
	s_setprio 1
	v_mfma_f32_16x16x32_bf16 v[124:127], v[144:147], v[160:163], v[124:127]
	v_mfma_f32_16x16x32_bf16 v[116:119], v[152:155], v[160:163], v[116:119]
	v_mfma_f32_16x16x32_bf16 v[100:103], v[144:147], v[168:171], v[100:103]
	v_mfma_f32_16x16x32_bf16 v[96:99], v[152:155], v[168:171], v[96:99]
	v_mfma_f32_16x16x32_bf16 v[84:87], v[144:147], v[186:189], v[84:87]
	v_mfma_f32_16x16x32_bf16 v[80:83], v[152:155], v[186:189], v[80:83]
	v_mfma_f32_16x16x32_bf16 v[68:71], v[144:147], v[202:205], v[68:71]
	v_mfma_f32_16x16x32_bf16 v[64:67], v[152:155], v[202:205], v[64:67]
	v_mfma_f32_16x16x32_bf16 v[124:127], v[148:151], v[164:167], v[124:127]
	v_mfma_f32_16x16x32_bf16 v[116:119], v[156:159], v[164:167], v[116:119]
	v_mfma_f32_16x16x32_bf16 v[100:103], v[148:151], v[172:175], v[100:103]
	v_mfma_f32_16x16x32_bf16 v[96:99], v[156:159], v[172:175], v[96:99]
	v_mfma_f32_16x16x32_bf16 v[84:87], v[148:151], v[198:201], v[84:87]
	v_mfma_f32_16x16x32_bf16 v[80:83], v[156:159], v[198:201], v[80:83]
	v_mfma_f32_16x16x32_bf16 v[68:71], v[148:151], v[206:209], v[68:71]
	v_mfma_f32_16x16x32_bf16 v[64:67], v[156:159], v[206:209], v[64:67]
	s_setprio 0
	s_barrier
	s_add_i32 s2, s30, s19
	s_mov_b32 m0, s2
	ds_read_b128 v[160:163], v231 offset:16384
	ds_read_b128 v[164:167], v231 offset:17408
	ds_read_b128 v[168:171], v231 offset:18432
	ds_read_b128 v[172:175], v231 offset:19456
	ds_read_b128 v[186:189], v231 offset:20480
	ds_read_b128 v[198:201], v231 offset:21504
	ds_read_b128 v[202:205], v231 offset:22528
	ds_read_b128 v[206:209], v231 offset:23552
	global_load_lds_dwordx4 v192, s[6:7]
	s_add_i32 m0, s2, 0x2000
	s_add_u32 s2, s6, 0x40000
	s_addc_u32 s3, s7, 0
	s_add_i32 s30, s31, s19
	global_load_lds_dwordx4 v176, s[6:7]
	s_mov_b32 m0, s30
	s_nop 0
	global_load_lds_dwordx4 v192, s[2:3]
	s_add_i32 m0, s30, 0x2000
	s_nop 0
	global_load_lds_dwordx4 v176, s[2:3]
	s_mov_b32 m0, s20
	s_nop 0
	global_load_lds_dwordx4 v180, s[84:85]
	s_mov_b32 m0, s21
	s_nop 0
	global_load_lds_dwordx4 v178, s[84:85]
	s_waitcnt vmcnt(8)
	s_waitcnt lgkmcnt(0)
	s_barrier
	s_setprio 1
	s_waitcnt lgkmcnt(0)
	v_mfma_f32_16x16x32_bf16 v[60:63], v[112:115], v[160:163], v[60:63]
	v_mfma_f32_16x16x32_bf16 v[56:59], v[128:131], v[160:163], v[56:59]
	v_mfma_f32_16x16x32_bf16 v[44:47], v[112:115], v[168:171], v[44:47]
	v_mfma_f32_16x16x32_bf16 v[40:43], v[128:131], v[168:171], v[40:43]
	v_mfma_f32_16x16x32_bf16 v[28:31], v[112:115], v[186:189], v[28:31]
	v_mfma_f32_16x16x32_bf16 v[24:27], v[128:131], v[186:189], v[24:27]
	v_mfma_f32_16x16x32_bf16 v[12:15], v[112:115], v[202:205], v[12:15]
	v_mfma_f32_16x16x32_bf16 v[8:11], v[128:131], v[202:205], v[8:11]
	v_mfma_f32_16x16x32_bf16 v[60:63], v[120:123], v[164:167], v[60:63]
	v_mfma_f32_16x16x32_bf16 v[56:59], v[140:143], v[164:167], v[56:59]
	v_mfma_f32_16x16x32_bf16 v[44:47], v[120:123], v[172:175], v[44:47]
	v_mfma_f32_16x16x32_bf16 v[40:43], v[140:143], v[172:175], v[40:43]
	v_mfma_f32_16x16x32_bf16 v[28:31], v[120:123], v[198:201], v[28:31]
	v_mfma_f32_16x16x32_bf16 v[24:27], v[140:143], v[198:201], v[24:27]
	v_mfma_f32_16x16x32_bf16 v[12:15], v[120:123], v[206:209], v[12:15]
	v_mfma_f32_16x16x32_bf16 v[8:11], v[140:143], v[206:209], v[8:11]
	s_setprio 0
	s_setprio 1
	v_mfma_f32_16x16x32_bf16 v[52:55], v[144:147], v[160:163], v[52:55]
	v_mfma_f32_16x16x32_bf16 v[48:51], v[152:155], v[160:163], v[48:51]
	v_mfma_f32_16x16x32_bf16 v[36:39], v[144:147], v[168:171], v[36:39]
	v_mfma_f32_16x16x32_bf16 v[32:35], v[152:155], v[168:171], v[32:35]
	v_mfma_f32_16x16x32_bf16 v[20:23], v[144:147], v[186:189], v[20:23]
	v_mfma_f32_16x16x32_bf16 v[16:19], v[152:155], v[186:189], v[16:19]
	v_mfma_f32_16x16x32_bf16 v[4:7], v[144:147], v[202:205], v[4:7]
	v_mfma_f32_16x16x32_bf16 v[0:3], v[152:155], v[202:205], v[0:3]
	v_mfma_f32_16x16x32_bf16 v[52:55], v[148:151], v[164:167], v[52:55]
	v_mfma_f32_16x16x32_bf16 v[48:51], v[156:159], v[164:167], v[48:51]
	v_mfma_f32_16x16x32_bf16 v[36:39], v[148:151], v[172:175], v[36:39]
	v_mfma_f32_16x16x32_bf16 v[32:35], v[156:159], v[172:175], v[32:35]
	v_mfma_f32_16x16x32_bf16 v[20:23], v[148:151], v[198:201], v[20:23]
	v_mfma_f32_16x16x32_bf16 v[16:19], v[156:159], v[198:201], v[16:19]
	v_mfma_f32_16x16x32_bf16 v[4:7], v[148:151], v[206:209], v[4:7]
	v_mfma_f32_16x16x32_bf16 v[0:3], v[156:159], v[206:209], v[0:3]
	s_setprio 0
	s_barrier
; #define PG8_STAGE(bufoff, gbase, voff) do { _Pragma("unroll") for (int _i = 0; _i < 2; ++_i) \
;         __builtin_amdgcn_global_load_lds((const unsigned*)((const char*)(gbase) + (voff)[_i]), (PG8_LAS unsigned*)(lds + (bufoff) + ldsw + _i * 8192), 16, 0, 0); } while (0)
; #define PG8_LDA(dst, b, h) do { _Pragma("unroll") for (int m = 0; m < 4; ++m) _Pragma("unroll") for (int k = 0; k < 2; ++k) dst[m][k] = *(const PG8_LAS bf16x8*)(lds + PG8_SA(b, h) + aoff + m * 2048 + k * 1024); } while (0)
; #define PG8_LDB(dst, b, h) do { _Pragma("unroll") for (int n = 0; n < 2; ++n) _Pragma("unroll") for (int k = 0; k < 2; ++k) dst[n][k] = *(const PG8_LAS bf16x8*)(lds + PG8_SB(b, h) + boff + n * 2048 + k * 1024); } while (0)
; #define PG8_MMA(ai, bj, At, Bt) do { __builtin_amdgcn_s_setprio(1); _Pragma("unroll") for (int m = 0; m < 4; ++m) _Pragma("unroll") for (int n = 0; n < 2; ++n) _Pragma("unroll") for (int k = 0; k < 2; ++k) \
;         acc[ai][bj][m][n] = __builtin_amdgcn_mfma_f32_16x16x32_bf16(Bt[n][k], At[m][k], acc[ai][bj][m][n], 0, 0, 0); __builtin_amdgcn_s_setprio(0); } while (0)
; #define PG8_WAIT_V(n) asm volatile("s_waitcnt vmcnt(" #n ")" ::: "memory")
; #define PG8_WAIT_L(n) asm volatile("s_waitcnt lgkmcnt(" #n ")" ::: "memory")
; #define PG8_BAR __builtin_amdgcn_s_barrier()
; #define PG8_SCHED __builtin_amdgcn_sched_barrier(0)
; template <class Epi, class Sched, bool ALIGN_EPI = false, bool SP2 = false>
; __device__ __forceinline__ void gemm_phase(PG8_LAS unsigned char* lds, const Gemm g, const Sched& S, const Epi& E) {
;     ...
;             PG8_LDB(B0, 1, 0); PG8_LDB(B1, 1, 1); PG8_SCHED; PG8_LDA(At, 1, 0); PG8_STAGE(PG8_SA(0, 1), a2 + hstepA, voffA);
;             PG8_WAIT_V(8); PG8_WAIT_L(0); PG8_BAR; PG8_MMA(0, 0, At, B0); PG8_MMA(0, 1, At, B1); PG8_BAR; PG8_SCHED;
;             PG8_LDA(At, 1, 1); PG8_STAGE(PG8_SB(1, 0), b3, voffB); PG8_STAGE(PG8_SB(1, 1), b3 + hstepB, voffB); PG8_STAGE(PG8_SA(1, 0), a3, voffA);
;             PG8_WAIT_V(8); PG8_WAIT_L(0); PG8_BAR; PG8_MMA(1, 0, At, B0); PG8_MMA(1, 1, At, B1); PG8_BAR; PG8_SCHED;
	s_add_i32 s30, 0, 0x18000
	s_add_i32 s31, 0, 0x1c000
	v_add_u32_e32 v140, s30, v230
	v_add_u32_e32 v156, s31, v230
	ds_read_b128 v[112:115], v140
	ds_read_b128 v[120:123], v140 offset:1024
	ds_read_b128 v[128:131], v140 offset:2048
	ds_read_b128 v[140:143], v140 offset:3072
	ds_read_b128 v[144:147], v156
	ds_read_b128 v[148:151], v156 offset:1024
	ds_read_b128 v[152:155], v156 offset:2048
	ds_read_b128 v[156:159], v156 offset:3072
	s_add_u32 s2, s84, 0x40000
	s_addc_u32 s3, s85, 0
	s_mov_b32 m0, s45
	ds_read_b128 v[160:163], v231 offset:32768
	ds_read_b128 v[164:167], v231 offset:33792
	ds_read_b128 v[168:171], v231 offset:34816
	ds_read_b128 v[172:175], v231 offset:35840
	ds_read_b128 v[186:189], v231 offset:36864
	ds_read_b128 v[198:201], v231 offset:37888
	ds_read_b128 v[202:205], v231 offset:38912
	ds_read_b128 v[206:209], v231 offset:39936
	global_load_lds_dwordx4 v180, s[2:3]
	s_mov_b32 m0, s49
	s_nop 0
	global_load_lds_dwordx4 v178, s[2:3]
	s_waitcnt vmcnt(8)
	s_waitcnt lgkmcnt(0)
	s_barrier
	s_setprio 1
	s_waitcnt lgkmcnt(0)
	v_mfma_f32_16x16x32_bf16 v[136:139], v[112:115], v[160:163], v[136:139]
	v_mfma_f32_16x16x32_bf16 v[132:135], v[128:131], v[160:163], v[132:135]
	v_mfma_f32_16x16x32_bf16 v[108:111], v[112:115], v[168:171], v[108:111]
	v_mfma_f32_16x16x32_bf16 v[104:107], v[128:131], v[168:171], v[104:107]
	v_mfma_f32_16x16x32_bf16 v[92:95], v[112:115], v[186:189], v[92:95]
	v_mfma_f32_16x16x32_bf16 v[88:91], v[128:131], v[186:189], v[88:91]
	v_mfma_f32_16x16x32_bf16 v[76:79], v[112:115], v[202:205], v[76:79]
	v_mfma_f32_16x16x32_bf16 v[72:75], v[128:131], v[202:205], v[72:75]
	v_mfma_f32_16x16x32_bf16 v[136:139], v[120:123], v[164:167], v[136:139]
	v_mfma_f32_16x16x32_bf16 v[132:135], v[140:143], v[164:167], v[132:135]
	v_mfma_f32_16x16x32_bf16 v[108:111], v[120:123], v[172:175], v[108:111]
	v_mfma_f32_16x16x32_bf16 v[104:107], v[140:143], v[172:175], v[104:107]
	v_mfma_f32_16x16x32_bf16 v[92:95], v[120:123], v[198:201], v[92:95]
	v_mfma_f32_16x16x32_bf16 v[88:91], v[140:143], v[198:201], v[88:91]
	v_mfma_f32_16x16x32_bf16 v[76:79], v[120:123], v[206:209], v[76:79]
	v_mfma_f32_16x16x32_bf16 v[72:75], v[140:143], v[206:209], v[72:75]
	s_setprio 0
	s_setprio 1
	v_mfma_f32_16x16x32_bf16 v[124:127], v[144:147], v[160:163], v[124:127]
	v_mfma_f32_16x16x32_bf16 v[116:119], v[152:155], v[160:163], v[116:119]
	v_mfma_f32_16x16x32_bf16 v[100:103], v[144:147], v[168:171], v[100:103]
	v_mfma_f32_16x16x32_bf16 v[96:99], v[152:155], v[168:171], v[96:99]
	v_mfma_f32_16x16x32_bf16 v[84:87], v[144:147], v[186:189], v[84:87]
	v_mfma_f32_16x16x32_bf16 v[80:83], v[152:155], v[186:189], v[80:83]
	v_mfma_f32_16x16x32_bf16 v[68:71], v[144:147], v[202:205], v[68:71]
	v_mfma_f32_16x16x32_bf16 v[64:67], v[152:155], v[202:205], v[64:67]
	v_mfma_f32_16x16x32_bf16 v[124:127], v[148:151], v[164:167], v[124:127]
	v_mfma_f32_16x16x32_bf16 v[116:119], v[156:159], v[164:167], v[116:119]
	v_mfma_f32_16x16x32_bf16 v[100:103], v[148:151], v[172:175], v[100:103]
	v_mfma_f32_16x16x32_bf16 v[96:99], v[156:159], v[172:175], v[96:99]
	v_mfma_f32_16x16x32_bf16 v[84:87], v[148:151], v[198:201], v[84:87]
	v_mfma_f32_16x16x32_bf16 v[80:83], v[156:159], v[198:201], v[80:83]
	v_mfma_f32_16x16x32_bf16 v[68:71], v[148:151], v[206:209], v[68:71]
	v_mfma_f32_16x16x32_bf16 v[64:67], v[156:159], v[206:209], v[64:67]
	s_setprio 0
	s_barrier
	s_add_i32 s2, s30, s19
	s_add_i32 m0, s2, 0xffffff80
	ds_read_b128 v[160:163], v231 offset:49152
	ds_read_b128 v[164:167], v231 offset:50176
	ds_read_b128 v[168:171], v231 offset:51200
	ds_read_b128 v[172:175], v231 offset:52224
	ds_read_b128 v[186:189], v231 offset:53248
	ds_read_b128 v[198:201], v231 offset:54272
	ds_read_b128 v[202:205], v231 offset:55296
	ds_read_b128 v[206:209], v231 offset:56320
	global_load_lds_dwordx4 v192, s[6:7] offset:128
	s_add_i32 m0, s2, 0x1f80
	s_add_u32 s2, s6, 0x40080
	global_load_lds_dwordx4 v176, s[6:7] offset:128
	s_addc_u32 s3, s7, 0
	s_add_i32 s6, s31, s19
	s_mov_b32 m0, s6
	s_nop 0
	global_load_lds_dwordx4 v192, s[2:3]
	s_add_i32 m0, s6, 0x2000
	s_nop 0
	global_load_lds_dwordx4 v176, s[2:3]
	s_add_i32 m0, s65, 0xffffff80
	s_nop 0
	global_load_lds_dwordx4 v180, s[84:85] offset:128
	s_add_i32 m0, s80, 0xffffff80
	s_nop 0
	global_load_lds_dwordx4 v178, s[84:85] offset:128
	s_waitcnt vmcnt(8)
	s_waitcnt lgkmcnt(0)
	s_barrier
	s_setprio 1
	s_waitcnt lgkmcnt(0)
	v_mfma_f32_16x16x32_bf16 v[60:63], v[112:115], v[160:163], v[60:63]
	v_mfma_f32_16x16x32_bf16 v[56:59], v[128:131], v[160:163], v[56:59]
	v_mfma_f32_16x16x32_bf16 v[44:47], v[112:115], v[168:171], v[44:47]
	v_mfma_f32_16x16x32_bf16 v[40:43], v[128:131], v[168:171], v[40:43]
	v_mfma_f32_16x16x32_bf16 v[28:31], v[112:115], v[186:189], v[28:31]
	v_mfma_f32_16x16x32_bf16 v[24:27], v[128:131], v[186:189], v[24:27]
	v_mfma_f32_16x16x32_bf16 v[12:15], v[112:115], v[202:205], v[12:15]
	v_mfma_f32_16x16x32_bf16 v[8:11], v[128:131], v[202:205], v[8:11]
	v_mfma_f32_16x16x32_bf16 v[60:63], v[120:123], v[164:167], v[60:63]
	v_mfma_f32_16x16x32_bf16 v[56:59], v[140:143], v[164:167], v[56:59]
	v_mfma_f32_16x16x32_bf16 v[44:47], v[120:123], v[172:175], v[44:47]
	v_mfma_f32_16x16x32_bf16 v[40:43], v[140:143], v[172:175], v[40:43]
	v_mfma_f32_16x16x32_bf16 v[28:31], v[120:123], v[198:201], v[28:31]
	v_mfma_f32_16x16x32_bf16 v[24:27], v[140:143], v[198:201], v[24:27]
	v_mfma_f32_16x16x32_bf16 v[12:15], v[120:123], v[206:209], v[12:15]
	v_mfma_f32_16x16x32_bf16 v[8:11], v[140:143], v[206:209], v[8:11]
	s_setprio 0
	s_setprio 1
	v_mfma_f32_16x16x32_bf16 v[52:55], v[144:147], v[160:163], v[52:55]
	v_mfma_f32_16x16x32_bf16 v[48:51], v[152:155], v[160:163], v[48:51]
	v_mfma_f32_16x16x32_bf16 v[36:39], v[144:147], v[168:171], v[36:39]
	v_mfma_f32_16x16x32_bf16 v[32:35], v[152:155], v[168:171], v[32:35]
	v_mfma_f32_16x16x32_bf16 v[20:23], v[144:147], v[186:189], v[20:23]
	v_mfma_f32_16x16x32_bf16 v[16:19], v[152:155], v[186:189], v[16:19]
	v_mfma_f32_16x16x32_bf16 v[4:7], v[144:147], v[202:205], v[4:7]
	v_mfma_f32_16x16x32_bf16 v[0:3], v[152:155], v[202:205], v[0:3]
	v_mfma_f32_16x16x32_bf16 v[52:55], v[148:151], v[164:167], v[52:55]
	v_mfma_f32_16x16x32_bf16 v[48:51], v[156:159], v[164:167], v[48:51]
	v_mfma_f32_16x16x32_bf16 v[36:39], v[148:151], v[172:175], v[36:39]
	v_mfma_f32_16x16x32_bf16 v[32:35], v[156:159], v[172:175], v[32:35]
	v_mfma_f32_16x16x32_bf16 v[20:23], v[148:151], v[198:201], v[20:23]
	v_mfma_f32_16x16x32_bf16 v[16:19], v[156:159], v[198:201], v[16:19]
	v_mfma_f32_16x16x32_bf16 v[4:7], v[148:151], v[206:209], v[4:7]
	v_mfma_f32_16x16x32_bf16 v[0:3], v[156:159], v[206:209], v[0:3]
	s_setprio 0
	s_barrier
	s_add_i32 s95, s95, 2
	s_add_u32 s93, s93, 0x100
	s_addc_u32 s94, s94, 0
	s_add_u32 s0, s0, 0x100
	s_addc_u32 s1, s1, 0
	s_cmp_gt_u32 s95, 13
	s_cbranch_scc0 .LBB0_634
	s_and_b64 vcc, exec, s[12:13]
	s_cbranch_vccz .LBB0_637
	s_barrier

; #define PG8_STAGE(bufoff, gbase, voff) do { _Pragma("unroll") for (int _i = 0; _i < 2; ++_i) \
;         __builtin_amdgcn_global_load_lds((const unsigned*)((const char*)(gbase) + (voff)[_i]), (PG8_LAS unsigned*)(lds + (bufoff) + ldsw + _i * 8192), 16, 0, 0); } while (0)
; #define PG8_LDA(dst, b, h) do { _Pragma("unroll") for (int m = 0; m < 4; ++m) _Pragma("unroll") for (int k = 0; k < 2; ++k) dst[m][k] = *(const PG8_LAS bf16x8*)(lds + PG8_SA(b, h) + aoff + m * 2048 + k * 1024); } while (0)
; #define PG8_LDB(dst, b, h) do { _Pragma("unroll") for (int n = 0; n < 2; ++n) _Pragma("unroll") for (int k = 0; k < 2; ++k) dst[n][k] = *(const PG8_LAS bf16x8*)(lds + PG8_SB(b, h) + boff + n * 2048 + k * 1024); } while (0)
; #define PG8_MMA(ai, bj, At, Bt) do { __builtin_amdgcn_s_setprio(1); _Pragma("unroll") for (int m = 0; m < 4; ++m) _Pragma("unroll") for (int n = 0; n < 2; ++n) _Pragma("unroll") for (int k = 0; k < 2; ++k) \
;         acc[ai][bj][m][n] = __builtin_amdgcn_mfma_f32_16x16x32_bf16(Bt[n][k], At[m][k], acc[ai][bj][m][n], 0, 0, 0); __builtin_amdgcn_s_setprio(0); } while (0)
; #define PG8_WAIT_V(n) asm volatile("s_waitcnt vmcnt(" #n ")" ::: "memory")
; #define PG8_WAIT_L(n) asm volatile("s_waitcnt lgkmcnt(" #n ")" ::: "memory")
; template <class Epi, class Sched, bool ALIGN_EPI = false, bool SP2 = false>
; __device__ __forceinline__ void gemm_phase(PG8_LAS unsigned char* lds, const Gemm g, const Sched& S, const Epi& E) {
;     ...
;             const bool last = (t == nt - 2);
;             const char* a1 = cA + (size_t)(t + 1) * kstep;
;             const char* a2 = last ? nA : cA + (size_t)(t + 2) * kstep; const char* b2 = last ? nB : cB + (size_t)(t + 2) * kstep;
;             const char* a3 = a2 + kstep; const char* b3 = b2 + kstep;
;             if (last && has_next) S.a_ready(nxt);
;             if constexpr (SP2) {
;             PG8_LDB(B0, 0, 0); PG8_LDB(B1, 0, 1); PG8_SCHED; PG8_LDA(At, 0, 0); PG8_STAGE(PG8_SA(1, 1), a1 + hstepA, voffA);
;             PG8_WAIT_V(8); PG8_WAIT_L(0); PG8_BAR; PG8_MMA(0, 0, At, B0); PG8_MMA(0, 1, At, B1); PG8_BAR; PG8_SCHED;
;             PG8_LDA(At, 0, 1); PG8_STAGE(PG8_SB(0, 0), b2, voffB); PG8_STAGE(PG8_SB(0, 1), b2 + hstepB, voffB); PG8_STAGE(PG8_SA(0, 0), a2, voffA);
;             PG8_WAIT_V(8); PG8_WAIT_L(0); PG8_BAR; PG8_MMA(1, 0, At, B0); PG8_MMA(1, 1, At, B1); PG8_BAR; PG8_SCHED;
.LBB0_693:
	s_add_u32 s2, s4, 0xfffc0080
	s_addc_u32 s3, s5, -1
	s_add_i32 s30, 0, 0x10000
	s_cmp_eq_u32 s92, 12
	s_cselect_b32 s87, s17, s3
	s_cselect_b32 s86, s78, s2
	s_cselect_b32 s85, s15, s91
	s_cselect_b32 s84, s89, s90
	s_add_i32 s31, 0, 0x14000
	v_add_u32_e32 v140, s30, v182
	v_add_u32_e32 v166, s31, v182
	ds_read_b128 v[128:131], v140
	ds_read_b128 v[132:135], v140 offset:1024
	ds_read_b128 v[136:139], v140 offset:2048
	ds_read_b128 v[140:143], v140 offset:3072
	ds_read_b128 v[144:147], v166
	ds_read_b128 v[148:151], v166 offset:1024
	ds_read_b128 v[152:155], v166 offset:2048
	ds_read_b128 v[166:169], v166 offset:3072
	s_add_i32 m0, s20, 0xc000
	ds_read_b128 v[170:173], v183
	ds_read_b128 v[174:177], v183 offset:1024
	ds_read_b128 v[178:181], v183 offset:2048
	ds_read_b128 v[184:187], v183 offset:3072
	ds_read_b128 v[188:191], v183 offset:4096
	ds_read_b128 v[198:201], v183 offset:5120
	ds_read_b128 v[202:205], v183 offset:6144
	ds_read_b128 v[206:209], v183 offset:7168
	global_load_lds_dwordx4 v164, s[4:5]
	s_add_i32 m0, s20, 0xe000
	s_nop 0
	global_load_lds_dwordx4 v162, s[4:5]
	s_waitcnt vmcnt(8)
	s_waitcnt lgkmcnt(0)
	s_barrier
	s_setprio 1
	s_waitcnt lgkmcnt(0)
	v_mfma_f32_16x16x32_bf16 v[124:127], v[128:131], v[170:173], v[124:127]
	v_mfma_f32_16x16x32_bf16 v[120:123], v[136:139], v[170:173], v[120:123]
	v_mfma_f32_16x16x32_bf16 v[108:111], v[128:131], v[178:181], v[108:111]
	v_mfma_f32_16x16x32_bf16 v[104:107], v[136:139], v[178:181], v[104:107]
	v_mfma_f32_16x16x32_bf16 v[92:95], v[128:131], v[188:191], v[92:95]
	v_mfma_f32_16x16x32_bf16 v[88:91], v[136:139], v[188:191], v[88:91]
	v_mfma_f32_16x16x32_bf16 v[76:79], v[128:131], v[202:205], v[76:79]
	v_mfma_f32_16x16x32_bf16 v[72:75], v[136:139], v[202:205], v[72:75]
	v_mfma_f32_16x16x32_bf16 v[124:127], v[132:135], v[174:177], v[124:127]
	v_mfma_f32_16x16x32_bf16 v[120:123], v[140:143], v[174:177], v[120:123]
	v_mfma_f32_16x16x32_bf16 v[108:111], v[132:135], v[184:187], v[108:111]
	v_mfma_f32_16x16x32_bf16 v[104:107], v[140:143], v[184:187], v[104:107]
	v_mfma_f32_16x16x32_bf16 v[92:95], v[132:135], v[198:201], v[92:95]
	v_mfma_f32_16x16x32_bf16 v[88:91], v[140:143], v[198:201], v[88:91]
	v_mfma_f32_16x16x32_bf16 v[76:79], v[132:135], v[206:209], v[76:79]
	v_mfma_f32_16x16x32_bf16 v[72:75], v[140:143], v[206:209], v[72:75]
	s_setprio 0
	s_setprio 1
	v_mfma_f32_16x16x32_bf16 v[116:119], v[144:147], v[170:173], v[116:119]
	v_mfma_f32_16x16x32_bf16 v[112:115], v[152:155], v[170:173], v[112:115]
	v_mfma_f32_16x16x32_bf16 v[100:103], v[144:147], v[178:181], v[100:103]
	v_mfma_f32_16x16x32_bf16 v[96:99], v[152:155], v[178:181], v[96:99]
	v_mfma_f32_16x16x32_bf16 v[84:87], v[144:147], v[188:191], v[84:87]
	v_mfma_f32_16x16x32_bf16 v[80:83], v[152:155], v[188:191], v[80:83]
	v_mfma_f32_16x16x32_bf16 v[68:71], v[144:147], v[202:205], v[68:71]
	v_mfma_f32_16x16x32_bf16 v[64:67], v[152:155], v[202:205], v[64:67]
	v_mfma_f32_16x16x32_bf16 v[116:119], v[148:151], v[174:177], v[116:119]
	v_mfma_f32_16x16x32_bf16 v[112:115], v[166:169], v[174:177], v[112:115]
	v_mfma_f32_16x16x32_bf16 v[100:103], v[148:151], v[184:187], v[100:103]
	v_mfma_f32_16x16x32_bf16 v[96:99], v[166:169], v[184:187], v[96:99]
	v_mfma_f32_16x16x32_bf16 v[84:87], v[148:151], v[198:201], v[84:87]
	v_mfma_f32_16x16x32_bf16 v[80:83], v[166:169], v[198:201], v[80:83]
	v_mfma_f32_16x16x32_bf16 v[68:71], v[148:151], v[206:209], v[68:71]
	v_mfma_f32_16x16x32_bf16 v[64:67], v[166:169], v[206:209], v[64:67]
	s_setprio 0
	s_barrier
	s_add_i32 s2, s30, s19
	s_mov_b32 m0, s2
	ds_read_b128 v[170:173], v183 offset:16384
	ds_read_b128 v[174:177], v183 offset:17408
	ds_read_b128 v[178:181], v183 offset:18432
	ds_read_b128 v[184:187], v183 offset:19456
	ds_read_b128 v[188:191], v183 offset:20480
	ds_read_b128 v[198:201], v183 offset:21504
	ds_read_b128 v[202:205], v183 offset:22528
	ds_read_b128 v[206:209], v183 offset:23552
	global_load_lds_dwordx4 v192, s[84:85]
	s_add_i32 m0, s2, 0x2000
	s_add_u32 s2, s84, 0x40000
	s_addc_u32 s3, s85, 0
	s_add_i32 s30, s31, s19
	global_load_lds_dwordx4 v156, s[84:85]
	s_mov_b32 m0, s30
	s_nop 0
	global_load_lds_dwordx4 v192, s[2:3]
	s_add_i32 m0, s30, 0x2000
	s_nop 0
	global_load_lds_dwordx4 v156, s[2:3]
	s_mov_b32 m0, s20
	s_nop 0
	global_load_lds_dwordx4 v160, s[86:87]
	s_mov_b32 m0, s21
	s_nop 0
	global_load_lds_dwordx4 v158, s[86:87]
	s_waitcnt vmcnt(8)
	s_waitcnt lgkmcnt(0)
	s_barrier
	s_setprio 1
	s_waitcnt lgkmcnt(0)
	v_mfma_f32_16x16x32_bf16 v[60:63], v[128:131], v[170:173], v[60:63]
	v_mfma_f32_16x16x32_bf16 v[56:59], v[136:139], v[170:173], v[56:59]
	v_mfma_f32_16x16x32_bf16 v[44:47], v[128:131], v[178:181], v[44:47]
	v_mfma_f32_16x16x32_bf16 v[40:43], v[136:139], v[178:181], v[40:43]
	v_mfma_f32_16x16x32_bf16 v[28:31], v[128:131], v[188:191], v[28:31]
	v_mfma_f32_16x16x32_bf16 v[24:27], v[136:139], v[188:191], v[24:27]
	v_mfma_f32_16x16x32_bf16 v[12:15], v[128:131], v[202:205], v[12:15]
	v_mfma_f32_16x16x32_bf16 v[8:11], v[136:139], v[202:205], v[8:11]
	v_mfma_f32_16x16x32_bf16 v[60:63], v[132:135], v[174:177], v[60:63]
	v_mfma_f32_16x16x32_bf16 v[56:59], v[140:143], v[174:177], v[56:59]
	v_mfma_f32_16x16x32_bf16 v[44:47], v[132:135], v[184:187], v[44:47]
	v_mfma_f32_16x16x32_bf16 v[40:43], v[140:143], v[184:187], v[40:43]
	v_mfma_f32_16x16x32_bf16 v[28:31], v[132:135], v[198:201], v[28:31]
	v_mfma_f32_16x16x32_bf16 v[24:27], v[140:143], v[198:201], v[24:27]
	v_mfma_f32_16x16x32_bf16 v[12:15], v[132:135], v[206:209], v[12:15]
	v_mfma_f32_16x16x32_bf16 v[8:11], v[140:143], v[206:209], v[8:11]
	s_setprio 0
	s_setprio 1
	v_mfma_f32_16x16x32_bf16 v[52:55], v[144:147], v[170:173], v[52:55]
	v_mfma_f32_16x16x32_bf16 v[48:51], v[152:155], v[170:173], v[48:51]
	v_mfma_f32_16x16x32_bf16 v[36:39], v[144:147], v[178:181], v[36:39]
	v_mfma_f32_16x16x32_bf16 v[32:35], v[152:155], v[178:181], v[32:35]
	v_mfma_f32_16x16x32_bf16 v[20:23], v[144:147], v[188:191], v[20:23]
	v_mfma_f32_16x16x32_bf16 v[16:19], v[152:155], v[188:191], v[16:19]
	v_mfma_f32_16x16x32_bf16 v[4:7], v[144:147], v[202:205], v[4:7]
	v_mfma_f32_16x16x32_bf16 v[0:3], v[152:155], v[202:205], v[0:3]
	v_mfma_f32_16x16x32_bf16 v[52:55], v[148:151], v[174:177], v[52:55]
	v_mfma_f32_16x16x32_bf16 v[48:51], v[166:169], v[174:177], v[48:51]
	v_mfma_f32_16x16x32_bf16 v[36:39], v[148:151], v[184:187], v[36:39]
	v_mfma_f32_16x16x32_bf16 v[32:35], v[166:169], v[184:187], v[32:35]
	v_mfma_f32_16x16x32_bf16 v[20:23], v[148:151], v[198:201], v[20:23]
	v_mfma_f32_16x16x32_bf16 v[16:19], v[166:169], v[198:201], v[16:19]
	v_mfma_f32_16x16x32_bf16 v[4:7], v[148:151], v[206:209], v[4:7]
	v_mfma_f32_16x16x32_bf16 v[0:3], v[166:169], v[206:209], v[0:3]
	s_setprio 0
	s_barrier
; #define PG8_STAGE(bufoff, gbase, voff) do { _Pragma("unroll") for (int _i = 0; _i < 2; ++_i) \
;         __builtin_amdgcn_global_load_lds((const unsigned*)((const char*)(gbase) + (voff)[_i]), (PG8_LAS unsigned*)(lds + (bufoff) + ldsw + _i * 8192), 16, 0, 0); } while (0)
; #define PG8_LDA(dst, b, h) do { _Pragma("unroll") for (int m = 0; m < 4; ++m) _Pragma("unroll") for (int k = 0; k < 2; ++k) dst[m][k] = *(const PG8_LAS bf16x8*)(lds + PG8_SA(b, h) + aoff + m * 2048 + k * 1024); } while (0)
; #define PG8_LDB(dst, b, h) do { _Pragma("unroll") for (int n = 0; n < 2; ++n) _Pragma("unroll") for (int k = 0; k < 2; ++k) dst[n][k] = *(const PG8_LAS bf16x8*)(lds + PG8_SB(b, h) + boff + n * 2048 + k * 1024); } while (0)
; #define PG8_MMA(ai, bj, At, Bt) do { __builtin_amdgcn_s_setprio(1); _Pragma("unroll") for (int m = 0; m < 4; ++m) _Pragma("unroll") for (int n = 0; n < 2; ++n) _Pragma("unroll") for (int k = 0; k < 2; ++k) \
;         acc[ai][bj][m][n] = __builtin_amdgcn_mfma_f32_16x16x32_bf16(Bt[n][k], At[m][k], acc[ai][bj][m][n], 0, 0, 0); __builtin_amdgcn_s_setprio(0); } while (0)
; #define PG8_WAIT_V(n) asm volatile("s_waitcnt vmcnt(" #n ")" ::: "memory")
; #define PG8_WAIT_L(n) asm volatile("s_waitcnt lgkmcnt(" #n ")" ::: "memory")
; #define PG8_BAR __builtin_amdgcn_s_barrier()
; #define PG8_SCHED __builtin_amdgcn_sched_barrier(0)
; template <class Epi, class Sched, bool ALIGN_EPI = false, bool SP2 = false>
; __device__ __forceinline__ void gemm_phase(PG8_LAS unsigned char* lds, const Gemm g, const Sched& S, const Epi& E) {
;     ...
;             PG8_LDB(B0, 1, 0); PG8_LDB(B1, 1, 1); PG8_SCHED; PG8_LDA(At, 1, 0); PG8_STAGE(PG8_SA(0, 1), a2 + hstepA, voffA);
;             PG8_WAIT_V(8); PG8_WAIT_L(0); PG8_BAR; PG8_MMA(0, 0, At, B0); PG8_MMA(0, 1, At, B1); PG8_BAR; PG8_SCHED;
;             PG8_LDA(At, 1, 1); PG8_STAGE(PG8_SB(1, 0), b3, voffB); PG8_STAGE(PG8_SB(1, 1), b3 + hstepB, voffB); PG8_STAGE(PG8_SA(1, 0), a3, voffA);
;             PG8_WAIT_V(8); PG8_WAIT_L(0); PG8_BAR; PG8_MMA(1, 0, At, B0); PG8_MMA(1, 1, At, B1); PG8_BAR; PG8_SCHED;
	s_add_i32 s30, 0, 0x18000
	s_add_i32 s31, 0, 0x1c000
	v_add_u32_e32 v140, s30, v182
	v_add_u32_e32 v166, s31, v182
	ds_read_b128 v[128:131], v140
	ds_read_b128 v[132:135], v140 offset:1024
	ds_read_b128 v[136:139], v140 offset:2048
	ds_read_b128 v[140:143], v140 offset:3072
	ds_read_b128 v[144:147], v166
	ds_read_b128 v[148:151], v166 offset:1024
	ds_read_b128 v[152:155], v166 offset:2048
	ds_read_b128 v[166:169], v166 offset:3072
	s_add_u32 s2, s86, 0x40000
	s_addc_u32 s3, s87, 0
	s_mov_b32 m0, s34
	ds_read_b128 v[170:173], v183 offset:32768
	ds_read_b128 v[174:177], v183 offset:33792
	ds_read_b128 v[178:181], v183 offset:34816
	ds_read_b128 v[184:187], v183 offset:35840
	ds_read_b128 v[188:191], v183 offset:36864
	ds_read_b128 v[198:201], v183 offset:37888
	ds_read_b128 v[202:205], v183 offset:38912
	ds_read_b128 v[206:209], v183 offset:39936
	global_load_lds_dwordx4 v160, s[2:3]
	s_mov_b32 m0, s45
	s_nop 0
	global_load_lds_dwordx4 v158, s[2:3]
	s_waitcnt vmcnt(8)
	s_waitcnt lgkmcnt(0)
	s_barrier
	s_setprio 1
	s_waitcnt lgkmcnt(0)
	v_mfma_f32_16x16x32_bf16 v[124:127], v[128:131], v[170:173], v[124:127]
	v_mfma_f32_16x16x32_bf16 v[120:123], v[136:139], v[170:173], v[120:123]
	v_mfma_f32_16x16x32_bf16 v[108:111], v[128:131], v[178:181], v[108:111]
	v_mfma_f32_16x16x32_bf16 v[104:107], v[136:139], v[178:181], v[104:107]
	v_mfma_f32_16x16x32_bf16 v[92:95], v[128:131], v[188:191], v[92:95]
	v_mfma_f32_16x16x32_bf16 v[88:91], v[136:139], v[188:191], v[88:91]
	v_mfma_f32_16x16x32_bf16 v[76:79], v[128:131], v[202:205], v[76:79]
	v_mfma_f32_16x16x32_bf16 v[72:75], v[136:139], v[202:205], v[72:75]
	v_mfma_f32_16x16x32_bf16 v[124:127], v[132:135], v[174:177], v[124:127]
	v_mfma_f32_16x16x32_bf16 v[120:123], v[140:143], v[174:177], v[120:123]
	v_mfma_f32_16x16x32_bf16 v[108:111], v[132:135], v[184:187], v[108:111]
	v_mfma_f32_16x16x32_bf16 v[104:107], v[140:143], v[184:187], v[104:107]
	v_mfma_f32_16x16x32_bf16 v[92:95], v[132:135], v[198:201], v[92:95]
	v_mfma_f32_16x16x32_bf16 v[88:91], v[140:143], v[198:201], v[88:91]
	v_mfma_f32_16x16x32_bf16 v[76:79], v[132:135], v[206:209], v[76:79]
	v_mfma_f32_16x16x32_bf16 v[72:75], v[140:143], v[206:209], v[72:75]
	s_setprio 0
	s_setprio 1
	v_mfma_f32_16x16x32_bf16 v[116:119], v[144:147], v[170:173], v[116:119]
	v_mfma_f32_16x16x32_bf16 v[112:115], v[152:155], v[170:173], v[112:115]
	v_mfma_f32_16x16x32_bf16 v[100:103], v[144:147], v[178:181], v[100:103]
	v_mfma_f32_16x16x32_bf16 v[96:99], v[152:155], v[178:181], v[96:99]
	v_mfma_f32_16x16x32_bf16 v[84:87], v[144:147], v[188:191], v[84:87]
	v_mfma_f32_16x16x32_bf16 v[80:83], v[152:155], v[188:191], v[80:83]
	v_mfma_f32_16x16x32_bf16 v[68:71], v[144:147], v[202:205], v[68:71]
	v_mfma_f32_16x16x32_bf16 v[64:67], v[152:155], v[202:205], v[64:67]
	v_mfma_f32_16x16x32_bf16 v[116:119], v[148:151], v[174:177], v[116:119]
	v_mfma_f32_16x16x32_bf16 v[112:115], v[166:169], v[174:177], v[112:115]
	v_mfma_f32_16x16x32_bf16 v[100:103], v[148:151], v[184:187], v[100:103]
	v_mfma_f32_16x16x32_bf16 v[96:99], v[166:169], v[184:187], v[96:99]
	v_mfma_f32_16x16x32_bf16 v[84:87], v[148:151], v[198:201], v[84:87]
	v_mfma_f32_16x16x32_bf16 v[80:83], v[166:169], v[198:201], v[80:83]
	v_mfma_f32_16x16x32_bf16 v[68:71], v[148:151], v[206:209], v[68:71]
	v_mfma_f32_16x16x32_bf16 v[64:67], v[166:169], v[206:209], v[64:67]
	s_setprio 0
	s_barrier
	s_add_i32 s2, s30, s19
	s_add_i32 m0, s2, 0xffffff80
	ds_read_b128 v[170:173], v183 offset:49152
	ds_read_b128 v[174:177], v183 offset:50176
	ds_read_b128 v[178:181], v183 offset:51200
	ds_read_b128 v[184:187], v183 offset:52224
	ds_read_b128 v[188:191], v183 offset:53248
	ds_read_b128 v[198:201], v183 offset:54272
	ds_read_b128 v[202:205], v183 offset:55296
	ds_read_b128 v[206:209], v183 offset:56320
	global_load_lds_dwordx4 v192, s[84:85] offset:128
	s_add_i32 m0, s2, 0x1f80
	s_add_u32 s2, s84, 0x40080
	s_addc_u32 s3, s85, 0
	s_add_i32 s30, s31, s19
	global_load_lds_dwordx4 v156, s[84:85] offset:128
	s_mov_b32 m0, s30
	s_nop 0
	global_load_lds_dwordx4 v192, s[2:3]
	s_add_i32 m0, s30, 0x2000
	s_nop 0
	global_load_lds_dwordx4 v156, s[2:3]
	s_add_i32 m0, s63, 0xffffff80
	s_nop 0
	global_load_lds_dwordx4 v160, s[86:87] offset:128
	s_add_i32 m0, s64, 0xffffff80
	s_nop 0
	global_load_lds_dwordx4 v158, s[86:87] offset:128
	s_waitcnt vmcnt(8)
	s_waitcnt lgkmcnt(0)
	s_barrier
	s_setprio 1
	s_waitcnt lgkmcnt(0)
	v_mfma_f32_16x16x32_bf16 v[60:63], v[128:131], v[170:173], v[60:63]
	v_mfma_f32_16x16x32_bf16 v[56:59], v[136:139], v[170:173], v[56:59]
	v_mfma_f32_16x16x32_bf16 v[44:47], v[128:131], v[178:181], v[44:47]
	v_mfma_f32_16x16x32_bf16 v[40:43], v[136:139], v[178:181], v[40:43]
	v_mfma_f32_16x16x32_bf16 v[28:31], v[128:131], v[188:191], v[28:31]
	v_mfma_f32_16x16x32_bf16 v[24:27], v[136:139], v[188:191], v[24:27]
	v_mfma_f32_16x16x32_bf16 v[12:15], v[128:131], v[202:205], v[12:15]
	v_mfma_f32_16x16x32_bf16 v[8:11], v[136:139], v[202:205], v[8:11]
	v_mfma_f32_16x16x32_bf16 v[60:63], v[132:135], v[174:177], v[60:63]
	v_mfma_f32_16x16x32_bf16 v[56:59], v[140:143], v[174:177], v[56:59]
	v_mfma_f32_16x16x32_bf16 v[44:47], v[132:135], v[184:187], v[44:47]
	v_mfma_f32_16x16x32_bf16 v[40:43], v[140:143], v[184:187], v[40:43]
	v_mfma_f32_16x16x32_bf16 v[28:31], v[132:135], v[198:201], v[28:31]
	v_mfma_f32_16x16x32_bf16 v[24:27], v[140:143], v[198:201], v[24:27]
	v_mfma_f32_16x16x32_bf16 v[12:15], v[132:135], v[206:209], v[12:15]
	v_mfma_f32_16x16x32_bf16 v[8:11], v[140:143], v[206:209], v[8:11]
	s_setprio 0
	s_setprio 1
	v_mfma_f32_16x16x32_bf16 v[52:55], v[144:147], v[170:173], v[52:55]
	v_mfma_f32_16x16x32_bf16 v[48:51], v[152:155], v[170:173], v[48:51]
	v_mfma_f32_16x16x32_bf16 v[36:39], v[144:147], v[178:181], v[36:39]
	v_mfma_f32_16x16x32_bf16 v[32:35], v[152:155], v[178:181], v[32:35]
	v_mfma_f32_16x16x32_bf16 v[20:23], v[144:147], v[188:191], v[20:23]
	v_mfma_f32_16x16x32_bf16 v[16:19], v[152:155], v[188:191], v[16:19]
	v_mfma_f32_16x16x32_bf16 v[4:7], v[144:147], v[202:205], v[4:7]
	v_mfma_f32_16x16x32_bf16 v[0:3], v[152:155], v[202:205], v[0:3]
	v_mfma_f32_16x16x32_bf16 v[52:55], v[148:151], v[174:177], v[52:55]
	v_mfma_f32_16x16x32_bf16 v[48:51], v[166:169], v[174:177], v[48:51]
	v_mfma_f32_16x16x32_bf16 v[36:39], v[148:151], v[184:187], v[36:39]
	v_mfma_f32_16x16x32_bf16 v[32:35], v[166:169], v[184:187], v[32:35]
	v_mfma_f32_16x16x32_bf16 v[20:23], v[148:151], v[198:201], v[20:23]
	v_mfma_f32_16x16x32_bf16 v[16:19], v[166:169], v[198:201], v[16:19]
	v_mfma_f32_16x16x32_bf16 v[4:7], v[148:151], v[206:209], v[4:7]
	v_mfma_f32_16x16x32_bf16 v[0:3], v[166:169], v[206:209], v[0:3]
	s_setprio 0
	s_barrier
	s_add_i32 s92, s92, 2
	s_add_u32 s90, s90, 0x100
	s_addc_u32 s91, s91, 0
	s_add_u32 s4, s4, 0x100
	s_addc_u32 s5, s5, 0
	s_cmp_gt_u32 s92, 13
	s_cbranch_scc0 .LBB0_693
	s_and_b64 vcc, exec, s[12:13]
	s_cbranch_vccz .LBB0_696
	s_barrier

; #define PG8_STAGE(bufoff, gbase, voff) do { _Pragma("unroll") for (int _i = 0; _i < 2; ++_i) \
;         __builtin_amdgcn_global_load_lds((const unsigned*)((const char*)(gbase) + (voff)[_i]), (PG8_LAS unsigned*)(lds + (bufoff) + ldsw + _i * 8192), 16, 0, 0); } while (0)
; #define PG8_LDA(dst, b, h) do { _Pragma("unroll") for (int m = 0; m < 4; ++m) _Pragma("unroll") for (int k = 0; k < 2; ++k) dst[m][k] = *(const PG8_LAS bf16x8*)(lds + PG8_SA(b, h) + aoff + m * 2048 + k * 1024); } while (0)
; #define PG8_LDB(dst, b, h) do { _Pragma("unroll") for (int n = 0; n < 2; ++n) _Pragma("unroll") for (int k = 0; k < 2; ++k) dst[n][k] = *(const PG8_LAS bf16x8*)(lds + PG8_SB(b, h) + boff + n * 2048 + k * 1024); } while (0)
; #define PG8_MMA(ai, bj, At, Bt) do { __builtin_amdgcn_s_setprio(1); _Pragma("unroll") for (int m = 0; m < 4; ++m) _Pragma("unroll") for (int n = 0; n < 2; ++n) _Pragma("unroll") for (int k = 0; k < 2; ++k) \
;         acc[ai][bj][m][n] = __builtin_amdgcn_mfma_f32_16x16x32_bf16(Bt[n][k], At[m][k], acc[ai][bj][m][n], 0, 0, 0); __builtin_amdgcn_s_setprio(0); } while (0)
; #define PG8_WAIT_V(n) asm volatile("s_waitcnt vmcnt(" #n ")" ::: "memory")
; #define PG8_WAIT_L(n) asm volatile("s_waitcnt lgkmcnt(" #n ")" ::: "memory")
; template <class Epi, class Sched, bool ALIGN_EPI = false, bool SP2 = false>
; __device__ __forceinline__ void gemm_phase(PG8_LAS unsigned char* lds, const Gemm g, const Sched& S, const Epi& E) {
;     ...
;             const bool last = (t == nt - 2);
;             const char* a1 = cA + (size_t)(t + 1) * kstep;
;             const char* a2 = last ? nA : cA + (size_t)(t + 2) * kstep; const char* b2 = last ? nB : cB + (size_t)(t + 2) * kstep;
;             const char* a3 = a2 + kstep; const char* b3 = b2 + kstep;
;             if (last && has_next) S.a_ready(nxt);
;             if constexpr (SP2) {
;             PG8_LDB(B0, 0, 0); PG8_LDB(B1, 0, 1); PG8_SCHED; PG8_LDA(At, 0, 0); PG8_STAGE(PG8_SA(1, 1), a1 + hstepA, voffA);
;             PG8_WAIT_V(8); PG8_WAIT_L(0); PG8_BAR; PG8_MMA(0, 0, At, B0); PG8_MMA(0, 1, At, B1); PG8_BAR; PG8_SCHED;
;             PG8_LDA(At, 0, 1); PG8_STAGE(PG8_SB(0, 0), b2, voffB); PG8_STAGE(PG8_SB(0, 1), b2 + hstepB, voffB); PG8_STAGE(PG8_SA(0, 0), a2, voffA);
;             PG8_WAIT_V(8); PG8_WAIT_L(0); PG8_BAR; PG8_MMA(1, 0, At, B0); PG8_MMA(1, 1, At, B1); PG8_BAR; PG8_SCHED;
.LBB0_724:
	s_add_i32 s2, s84, 2
	s_add_u32 s3, s82, 0x80
	s_addc_u32 s30, s83, 0
	s_add_i32 s77, 0, 0x10000
	s_cmp_eq_u32 s93, s84
	s_cselect_b32 s85, s5, s30
	s_cselect_b32 s84, s4, s3
	s_cselect_b32 s31, s67, vcc_hi
	s_cselect_b32 s30, s66, vcc_lo
	s_add_i32 s3, 0, 0x14000
	v_add_u32_e32 v136, s77, v247
	v_add_u32_e32 v156, s3, v247
	ds_read_b128 v[112:115], v136
	ds_read_b128 v[124:127], v136 offset:1024
	ds_read_b128 v[128:131], v136 offset:2048
	ds_read_b128 v[136:139], v136 offset:3072
	ds_read_b128 v[144:147], v156
	ds_read_b128 v[148:151], v156 offset:1024
	ds_read_b128 v[152:155], v156 offset:2048
	ds_read_b128 v[156:159], v156 offset:3072
	s_add_i32 m0, s64, 0xc000
	ds_read_b128 v[160:163], v248
	ds_read_b128 v[164:167], v248 offset:1024
	ds_read_b128 v[168:171], v248 offset:2048
	ds_read_b128 v[172:175], v248 offset:3072
	ds_read_b128 v[176:179], v248 offset:4096
	ds_read_b128 v[180:183], v248 offset:5120
	ds_read_b128 v[184:187], v248 offset:6144
	ds_read_b128 v[188:191], v248 offset:7168
	global_load_lds_dwordx4 v206, s[82:83]
	s_add_i32 m0, s64, 0xe000
	s_nop 0
	global_load_lds_dwordx4 v204, s[82:83]
	s_waitcnt vmcnt(8)
	s_waitcnt lgkmcnt(0)
	s_barrier
	s_setprio 1
	s_waitcnt lgkmcnt(0)
	v_mfma_f32_16x16x32_bf16 v[140:143], v[112:115], v[160:163], v[140:143]
	v_mfma_f32_16x16x32_bf16 v[132:135], v[128:131], v[160:163], v[132:135]
	v_mfma_f32_16x16x32_bf16 v[108:111], v[112:115], v[168:171], v[108:111]
	v_mfma_f32_16x16x32_bf16 v[104:107], v[128:131], v[168:171], v[104:107]
	v_mfma_f32_16x16x32_bf16 v[92:95], v[112:115], v[176:179], v[92:95]
	v_mfma_f32_16x16x32_bf16 v[88:91], v[128:131], v[176:179], v[88:91]
	v_mfma_f32_16x16x32_bf16 v[76:79], v[112:115], v[184:187], v[76:79]
	v_mfma_f32_16x16x32_bf16 v[72:75], v[128:131], v[184:187], v[72:75]
	v_mfma_f32_16x16x32_bf16 v[140:143], v[124:127], v[164:167], v[140:143]
	v_mfma_f32_16x16x32_bf16 v[132:135], v[136:139], v[164:167], v[132:135]
	v_mfma_f32_16x16x32_bf16 v[108:111], v[124:127], v[172:175], v[108:111]
	v_mfma_f32_16x16x32_bf16 v[104:107], v[136:139], v[172:175], v[104:107]
	v_mfma_f32_16x16x32_bf16 v[92:95], v[124:127], v[180:183], v[92:95]
	v_mfma_f32_16x16x32_bf16 v[88:91], v[136:139], v[180:183], v[88:91]
	v_mfma_f32_16x16x32_bf16 v[76:79], v[124:127], v[188:191], v[76:79]
	v_mfma_f32_16x16x32_bf16 v[72:75], v[136:139], v[188:191], v[72:75]
	s_setprio 0
	s_setprio 1
	v_mfma_f32_16x16x32_bf16 v[120:123], v[144:147], v[160:163], v[120:123]
	v_mfma_f32_16x16x32_bf16 v[116:119], v[152:155], v[160:163], v[116:119]
	v_mfma_f32_16x16x32_bf16 v[100:103], v[144:147], v[168:171], v[100:103]
	v_mfma_f32_16x16x32_bf16 v[96:99], v[152:155], v[168:171], v[96:99]
	v_mfma_f32_16x16x32_bf16 v[84:87], v[144:147], v[176:179], v[84:87]
	v_mfma_f32_16x16x32_bf16 v[80:83], v[152:155], v[176:179], v[80:83]
	v_mfma_f32_16x16x32_bf16 v[68:71], v[144:147], v[184:187], v[68:71]
	v_mfma_f32_16x16x32_bf16 v[64:67], v[152:155], v[184:187], v[64:67]
	v_mfma_f32_16x16x32_bf16 v[120:123], v[148:151], v[164:167], v[120:123]
	v_mfma_f32_16x16x32_bf16 v[116:119], v[156:159], v[164:167], v[116:119]
	v_mfma_f32_16x16x32_bf16 v[100:103], v[148:151], v[172:175], v[100:103]
	v_mfma_f32_16x16x32_bf16 v[96:99], v[156:159], v[172:175], v[96:99]
	v_mfma_f32_16x16x32_bf16 v[84:87], v[148:151], v[180:183], v[84:87]
	v_mfma_f32_16x16x32_bf16 v[80:83], v[156:159], v[180:183], v[80:83]
	v_mfma_f32_16x16x32_bf16 v[68:71], v[148:151], v[188:191], v[68:71]
	v_mfma_f32_16x16x32_bf16 v[64:67], v[156:159], v[188:191], v[64:67]
	s_setprio 0
	s_barrier
	s_add_i32 s77, s77, s63
	v_lshl_add_u64 v[208:209], s[30:31], 0, v[192:193]
	s_mov_b32 m0, s77
	ds_read_b128 v[160:163], v248 offset:16384
	ds_read_b128 v[164:167], v248 offset:17408
	ds_read_b128 v[168:171], v248 offset:18432
	ds_read_b128 v[172:175], v248 offset:19456
	ds_read_b128 v[176:179], v248 offset:20480
	ds_read_b128 v[180:183], v248 offset:21504
	ds_read_b128 v[184:187], v248 offset:22528
	ds_read_b128 v[188:191], v248 offset:23552
	global_load_lds_dwordx4 v192, s[30:31]
	s_add_i32 m0, s77, 0x2000
	v_lshl_add_u64 v[210:211], s[30:31], 0, v[198:199]
	global_load_lds_dwordx4 v198, s[30:31]
	s_add_u32 s30, s30, s45
	s_addc_u32 s31, s31, 0
	s_add_i32 s3, s3, s63
	v_lshl_add_u64 v[212:213], s[30:31], 0, v[192:193]
	s_mov_b32 m0, s3
	v_lshl_add_u64 v[214:215], s[30:31], 0, v[198:199]
	global_load_lds_dwordx4 v192, s[30:31]
	s_add_i32 m0, s3, 0x2000
	s_nop 0
	global_load_lds_dwordx4 v198, s[30:31]
	s_mov_b32 m0, s64
	s_nop 0
	global_load_lds_dwordx4 v202, s[84:85]
	s_mov_b32 m0, s65
	s_nop 0
	global_load_lds_dwordx4 v200, s[84:85]
	s_waitcnt vmcnt(8)
	s_waitcnt lgkmcnt(0)
	s_barrier
; #define PG8_STAGE(bufoff, gbase, voff) do { _Pragma("unroll") for (int _i = 0; _i < 2; ++_i) \
;         __builtin_amdgcn_global_load_lds((const unsigned*)((const char*)(gbase) + (voff)[_i]), (PG8_LAS unsigned*)(lds + (bufoff) + ldsw + _i * 8192), 16, 0, 0); } while (0)
; #define PG8_LDA(dst, b, h) do { _Pragma("unroll") for (int m = 0; m < 4; ++m) _Pragma("unroll") for (int k = 0; k < 2; ++k) dst[m][k] = *(const PG8_LAS bf16x8*)(lds + PG8_SA(b, h) + aoff + m * 2048 + k * 1024); } while (0)
; #define PG8_LDB(dst, b, h) do { _Pragma("unroll") for (int n = 0; n < 2; ++n) _Pragma("unroll") for (int k = 0; k < 2; ++k) dst[n][k] = *(const PG8_LAS bf16x8*)(lds + PG8_SB(b, h) + boff + n * 2048 + k * 1024); } while (0)
; #define PG8_MMA(ai, bj, At, Bt) do { __builtin_amdgcn_s_setprio(1); _Pragma("unroll") for (int m = 0; m < 4; ++m) _Pragma("unroll") for (int n = 0; n < 2; ++n) _Pragma("unroll") for (int k = 0; k < 2; ++k) \
;         acc[ai][bj][m][n] = __builtin_amdgcn_mfma_f32_16x16x32_bf16(Bt[n][k], At[m][k], acc[ai][bj][m][n], 0, 0, 0); __builtin_amdgcn_s_setprio(0); } while (0)
; #define PG8_WAIT_V(n) asm volatile("s_waitcnt vmcnt(" #n ")" ::: "memory")
; #define PG8_WAIT_L(n) asm volatile("s_waitcnt lgkmcnt(" #n ")" ::: "memory")
; #define PG8_BAR __builtin_amdgcn_s_barrier()
; #define PG8_SCHED __builtin_amdgcn_sched_barrier(0)
; template <class Epi, class Sched, bool ALIGN_EPI = false, bool SP2 = false>
; __device__ __forceinline__ void gemm_phase(PG8_LAS unsigned char* lds, const Gemm g, const Sched& S, const Epi& E) {
;     ...
;             PG8_WAIT_V(8); PG8_WAIT_L(0); PG8_BAR; PG8_MMA(1, 0, At, B0); PG8_MMA(1, 1, At, B1); PG8_BAR; PG8_SCHED;
;             PG8_LDB(B0, 1, 0); PG8_LDB(B1, 1, 1); PG8_SCHED; PG8_LDA(At, 1, 0); PG8_STAGE(PG8_SA(0, 1), a2 + hstepA, voffA);
;             PG8_WAIT_V(8); PG8_WAIT_L(0); PG8_BAR; PG8_MMA(0, 0, At, B0); PG8_MMA(0, 1, At, B1); PG8_BAR; PG8_SCHED;
	s_setprio 1
	s_waitcnt lgkmcnt(0)
	v_mfma_f32_16x16x32_bf16 v[60:63], v[112:115], v[160:163], v[60:63]
	v_mfma_f32_16x16x32_bf16 v[56:59], v[128:131], v[160:163], v[56:59]
	v_mfma_f32_16x16x32_bf16 v[44:47], v[112:115], v[168:171], v[44:47]
	v_mfma_f32_16x16x32_bf16 v[40:43], v[128:131], v[168:171], v[40:43]
	v_mfma_f32_16x16x32_bf16 v[28:31], v[112:115], v[176:179], v[28:31]
	v_mfma_f32_16x16x32_bf16 v[24:27], v[128:131], v[176:179], v[24:27]
	v_mfma_f32_16x16x32_bf16 v[12:15], v[112:115], v[184:187], v[12:15]
	v_mfma_f32_16x16x32_bf16 v[8:11], v[128:131], v[184:187], v[8:11]
	v_mfma_f32_16x16x32_bf16 v[60:63], v[124:127], v[164:167], v[60:63]
	v_mfma_f32_16x16x32_bf16 v[56:59], v[136:139], v[164:167], v[56:59]
	v_mfma_f32_16x16x32_bf16 v[44:47], v[124:127], v[172:175], v[44:47]
	v_mfma_f32_16x16x32_bf16 v[40:43], v[136:139], v[172:175], v[40:43]
	v_mfma_f32_16x16x32_bf16 v[28:31], v[124:127], v[180:183], v[28:31]
	v_mfma_f32_16x16x32_bf16 v[24:27], v[136:139], v[180:183], v[24:27]
	v_mfma_f32_16x16x32_bf16 v[12:15], v[124:127], v[188:191], v[12:15]
	v_mfma_f32_16x16x32_bf16 v[8:11], v[136:139], v[188:191], v[8:11]
	s_setprio 0
	s_setprio 1
	v_mfma_f32_16x16x32_bf16 v[52:55], v[144:147], v[160:163], v[52:55]
	v_mfma_f32_16x16x32_bf16 v[48:51], v[152:155], v[160:163], v[48:51]
	v_mfma_f32_16x16x32_bf16 v[36:39], v[144:147], v[168:171], v[36:39]
	v_mfma_f32_16x16x32_bf16 v[32:35], v[152:155], v[168:171], v[32:35]
	v_mfma_f32_16x16x32_bf16 v[20:23], v[144:147], v[176:179], v[20:23]
	v_mfma_f32_16x16x32_bf16 v[16:19], v[152:155], v[176:179], v[16:19]
	v_mfma_f32_16x16x32_bf16 v[4:7], v[144:147], v[184:187], v[4:7]
	v_mfma_f32_16x16x32_bf16 v[0:3], v[152:155], v[184:187], v[0:3]
	v_mfma_f32_16x16x32_bf16 v[52:55], v[148:151], v[164:167], v[52:55]
	v_mfma_f32_16x16x32_bf16 v[48:51], v[156:159], v[164:167], v[48:51]
	v_mfma_f32_16x16x32_bf16 v[36:39], v[148:151], v[172:175], v[36:39]
	v_mfma_f32_16x16x32_bf16 v[32:35], v[156:159], v[172:175], v[32:35]
	v_mfma_f32_16x16x32_bf16 v[20:23], v[148:151], v[180:183], v[20:23]
	v_mfma_f32_16x16x32_bf16 v[16:19], v[156:159], v[180:183], v[16:19]
	v_mfma_f32_16x16x32_bf16 v[4:7], v[148:151], v[188:191], v[4:7]
	v_mfma_f32_16x16x32_bf16 v[0:3], v[156:159], v[188:191], v[0:3]
	s_setprio 0
	s_barrier
	s_add_i32 s3, 0, 0x18000
	s_add_i32 s77, 0, 0x1c000
	v_add_u32_e32 v136, s3, v247
	v_add_u32_e32 v156, s77, v247
	ds_read_b128 v[112:115], v136
	ds_read_b128 v[124:127], v136 offset:1024
	ds_read_b128 v[128:131], v136 offset:2048
	ds_read_b128 v[136:139], v136 offset:3072
	ds_read_b128 v[144:147], v156
	ds_read_b128 v[148:151], v156 offset:1024
	ds_read_b128 v[152:155], v156 offset:2048
	ds_read_b128 v[156:159], v156 offset:3072
	s_add_u32 s30, s84, s10
	s_addc_u32 s31, s85, 0
	s_mov_b32 m0, s80
	ds_read_b128 v[160:163], v248 offset:32768
	ds_read_b128 v[164:167], v248 offset:33792
	ds_read_b128 v[168:171], v248 offset:34816
	ds_read_b128 v[172:175], v248 offset:35840
	ds_read_b128 v[176:179], v248 offset:36864
	ds_read_b128 v[180:183], v248 offset:37888
	ds_read_b128 v[184:187], v248 offset:38912
	ds_read_b128 v[188:191], v248 offset:39936
	global_load_lds_dwordx4 v202, s[30:31]
	s_mov_b32 m0, s86
	s_nop 0
	global_load_lds_dwordx4 v200, s[30:31]
	s_waitcnt vmcnt(8)
	s_waitcnt lgkmcnt(0)
	s_barrier
	s_setprio 1
	s_waitcnt lgkmcnt(0)
	v_mfma_f32_16x16x32_bf16 v[140:143], v[112:115], v[160:163], v[140:143]
	v_mfma_f32_16x16x32_bf16 v[132:135], v[128:131], v[160:163], v[132:135]
	v_mfma_f32_16x16x32_bf16 v[108:111], v[112:115], v[168:171], v[108:111]
	v_mfma_f32_16x16x32_bf16 v[104:107], v[128:131], v[168:171], v[104:107]
	v_mfma_f32_16x16x32_bf16 v[92:95], v[112:115], v[176:179], v[92:95]
	v_mfma_f32_16x16x32_bf16 v[88:91], v[128:131], v[176:179], v[88:91]
	v_mfma_f32_16x16x32_bf16 v[76:79], v[112:115], v[184:187], v[76:79]
	v_mfma_f32_16x16x32_bf16 v[72:75], v[128:131], v[184:187], v[72:75]
	v_mfma_f32_16x16x32_bf16 v[140:143], v[124:127], v[164:167], v[140:143]
	v_mfma_f32_16x16x32_bf16 v[132:135], v[136:139], v[164:167], v[132:135]
	v_mfma_f32_16x16x32_bf16 v[108:111], v[124:127], v[172:175], v[108:111]
	v_mfma_f32_16x16x32_bf16 v[104:107], v[136:139], v[172:175], v[104:107]
	v_mfma_f32_16x16x32_bf16 v[92:95], v[124:127], v[180:183], v[92:95]
	v_mfma_f32_16x16x32_bf16 v[88:91], v[136:139], v[180:183], v[88:91]
	v_mfma_f32_16x16x32_bf16 v[76:79], v[124:127], v[188:191], v[76:79]
	v_mfma_f32_16x16x32_bf16 v[72:75], v[136:139], v[188:191], v[72:75]
	s_setprio 0
	s_setprio 1
	v_mfma_f32_16x16x32_bf16 v[120:123], v[144:147], v[160:163], v[120:123]
	v_mfma_f32_16x16x32_bf16 v[116:119], v[152:155], v[160:163], v[116:119]
	v_mfma_f32_16x16x32_bf16 v[100:103], v[144:147], v[168:171], v[100:103]
	v_mfma_f32_16x16x32_bf16 v[96:99], v[152:155], v[168:171], v[96:99]
	v_mfma_f32_16x16x32_bf16 v[84:87], v[144:147], v[176:179], v[84:87]
	v_mfma_f32_16x16x32_bf16 v[80:83], v[152:155], v[176:179], v[80:83]
	v_mfma_f32_16x16x32_bf16 v[68:71], v[144:147], v[184:187], v[68:71]
	v_mfma_f32_16x16x32_bf16 v[64:67], v[152:155], v[184:187], v[64:67]
	v_mfma_f32_16x16x32_bf16 v[120:123], v[148:151], v[164:167], v[120:123]
	v_mfma_f32_16x16x32_bf16 v[116:119], v[156:159], v[164:167], v[116:119]
	v_mfma_f32_16x16x32_bf16 v[100:103], v[148:151], v[172:175], v[100:103]
	v_mfma_f32_16x16x32_bf16 v[96:99], v[156:159], v[172:175], v[96:99]
	v_mfma_f32_16x16x32_bf16 v[84:87], v[148:151], v[180:183], v[84:87]
	v_mfma_f32_16x16x32_bf16 v[80:83], v[156:159], v[180:183], v[80:83]
	v_mfma_f32_16x16x32_bf16 v[68:71], v[148:151], v[188:191], v[68:71]
	v_mfma_f32_16x16x32_bf16 v[64:67], v[156:159], v[188:191], v[64:67]
	s_setprio 0
	s_barrier
; #define PG8_STAGE(bufoff, gbase, voff) do { _Pragma("unroll") for (int _i = 0; _i < 2; ++_i) \
;         __builtin_amdgcn_global_load_lds((const unsigned*)((const char*)(gbase) + (voff)[_i]), (PG8_LAS unsigned*)(lds + (bufoff) + ldsw + _i * 8192), 16, 0, 0); } while (0)
; #define PG8_LDA(dst, b, h) do { _Pragma("unroll") for (int m = 0; m < 4; ++m) _Pragma("unroll") for (int k = 0; k < 2; ++k) dst[m][k] = *(const PG8_LAS bf16x8*)(lds + PG8_SA(b, h) + aoff + m * 2048 + k * 1024); } while (0)
; #define PG8_MMA(ai, bj, At, Bt) do { __builtin_amdgcn_s_setprio(1); _Pragma("unroll") for (int m = 0; m < 4; ++m) _Pragma("unroll") for (int n = 0; n < 2; ++n) _Pragma("unroll") for (int k = 0; k < 2; ++k) \
;         acc[ai][bj][m][n] = __builtin_amdgcn_mfma_f32_16x16x32_bf16(Bt[n][k], At[m][k], acc[ai][bj][m][n], 0, 0, 0); __builtin_amdgcn_s_setprio(0); } while (0)
; #define PG8_WAIT_V(n) asm volatile("s_waitcnt vmcnt(" #n ")" ::: "memory")
; #define PG8_WAIT_L(n) asm volatile("s_waitcnt lgkmcnt(" #n ")" ::: "memory")
; #define PG8_BAR __builtin_amdgcn_s_barrier()
; #define PG8_SCHED __builtin_amdgcn_sched_barrier(0)
; template <class Epi, class Sched, bool ALIGN_EPI = false, bool SP2 = false>
; __device__ __forceinline__ void gemm_phase(PG8_LAS unsigned char* lds, const Gemm g, const Sched& S, const Epi& E) {
;     ...
;             PG8_LDA(At, 1, 1); PG8_STAGE(PG8_SB(1, 0), b3, voffB); PG8_STAGE(PG8_SB(1, 1), b3 + hstepB, voffB); PG8_STAGE(PG8_SA(1, 0), a3, voffA);
;             PG8_WAIT_V(8); PG8_WAIT_L(0); PG8_BAR; PG8_MMA(1, 0, At, B0); PG8_MMA(1, 1, At, B1); PG8_BAR; PG8_SCHED;
	s_add_i32 s3, s3, s63
	v_lshl_add_u64 v[208:209], v[208:209], 0, s[36:37]
	s_mov_b32 m0, s3
	ds_read_b128 v[160:163], v248 offset:49152
	ds_read_b128 v[164:167], v248 offset:50176
	ds_read_b128 v[168:171], v248 offset:51200
	ds_read_b128 v[172:175], v248 offset:52224
	ds_read_b128 v[176:179], v248 offset:53248
	ds_read_b128 v[180:183], v248 offset:54272
	ds_read_b128 v[184:187], v248 offset:55296
	ds_read_b128 v[188:191], v248 offset:56320
	global_load_lds_dwordx4 v[208:209], off
	v_lshl_add_u64 v[208:209], v[210:211], 0, s[36:37]
	s_add_i32 m0, s3, 0x2000
	s_add_i32 s3, s77, s63
	global_load_lds_dwordx4 v[208:209], off
	v_lshl_add_u64 v[208:209], v[212:213], 0, s[36:37]
	s_mov_b32 m0, s3
	s_nop 0
	global_load_lds_dwordx4 v[208:209], off
	v_lshl_add_u64 v[208:209], v[214:215], 0, s[36:37]
	s_add_i32 m0, s3, 0x2000
	s_nop 0
	global_load_lds_dwordx4 v[208:209], off
	s_add_i32 m0, s91, 0xffffff80
	s_nop 0
	global_load_lds_dwordx4 v202, s[84:85] offset:128
	s_add_i32 m0, s92, 0xffffff80
	s_nop 0
	global_load_lds_dwordx4 v200, s[84:85] offset:128
	s_waitcnt vmcnt(8)
	s_waitcnt lgkmcnt(0)
	s_barrier
	s_setprio 1
	s_waitcnt lgkmcnt(0)
	v_mfma_f32_16x16x32_bf16 v[60:63], v[112:115], v[160:163], v[60:63]
	v_mfma_f32_16x16x32_bf16 v[56:59], v[128:131], v[160:163], v[56:59]
	v_mfma_f32_16x16x32_bf16 v[44:47], v[112:115], v[168:171], v[44:47]
	v_mfma_f32_16x16x32_bf16 v[40:43], v[128:131], v[168:171], v[40:43]
	v_mfma_f32_16x16x32_bf16 v[28:31], v[112:115], v[176:179], v[28:31]
	v_mfma_f32_16x16x32_bf16 v[24:27], v[128:131], v[176:179], v[24:27]
	v_mfma_f32_16x16x32_bf16 v[12:15], v[112:115], v[184:187], v[12:15]
	v_mfma_f32_16x16x32_bf16 v[8:11], v[128:131], v[184:187], v[8:11]
	v_mfma_f32_16x16x32_bf16 v[60:63], v[124:127], v[164:167], v[60:63]
	v_mfma_f32_16x16x32_bf16 v[56:59], v[136:139], v[164:167], v[56:59]
	v_mfma_f32_16x16x32_bf16 v[44:47], v[124:127], v[172:175], v[44:47]
	v_mfma_f32_16x16x32_bf16 v[40:43], v[136:139], v[172:175], v[40:43]
	v_mfma_f32_16x16x32_bf16 v[28:31], v[124:127], v[180:183], v[28:31]
	v_mfma_f32_16x16x32_bf16 v[24:27], v[136:139], v[180:183], v[24:27]
	v_mfma_f32_16x16x32_bf16 v[12:15], v[124:127], v[188:191], v[12:15]
	v_mfma_f32_16x16x32_bf16 v[8:11], v[136:139], v[188:191], v[8:11]
	s_setprio 0
	s_setprio 1
	v_mfma_f32_16x16x32_bf16 v[52:55], v[144:147], v[160:163], v[52:55]
	v_mfma_f32_16x16x32_bf16 v[48:51], v[152:155], v[160:163], v[48:51]
	v_mfma_f32_16x16x32_bf16 v[36:39], v[144:147], v[168:171], v[36:39]
	v_mfma_f32_16x16x32_bf16 v[32:35], v[152:155], v[168:171], v[32:35]
	v_mfma_f32_16x16x32_bf16 v[20:23], v[144:147], v[176:179], v[20:23]
	v_mfma_f32_16x16x32_bf16 v[16:19], v[152:155], v[176:179], v[16:19]
	v_mfma_f32_16x16x32_bf16 v[4:7], v[144:147], v[184:187], v[4:7]
	v_mfma_f32_16x16x32_bf16 v[0:3], v[152:155], v[184:187], v[0:3]
	v_mfma_f32_16x16x32_bf16 v[52:55], v[148:151], v[164:167], v[52:55]
	v_mfma_f32_16x16x32_bf16 v[48:51], v[156:159], v[164:167], v[48:51]
	v_mfma_f32_16x16x32_bf16 v[36:39], v[148:151], v[172:175], v[36:39]
	v_mfma_f32_16x16x32_bf16 v[32:35], v[156:159], v[172:175], v[32:35]
	v_mfma_f32_16x16x32_bf16 v[20:23], v[148:151], v[180:183], v[20:23]
	v_mfma_f32_16x16x32_bf16 v[16:19], v[156:159], v[180:183], v[16:19]
	v_mfma_f32_16x16x32_bf16 v[4:7], v[148:151], v[188:191], v[4:7]
	v_mfma_f32_16x16x32_bf16 v[0:3], v[156:159], v[188:191], v[0:3]
	s_setprio 0
	s_barrier
	s_add_u32 vcc_lo, vcc_lo, 0x100
	s_addc_u32 vcc_hi, vcc_hi, 0
	s_add_u32 s82, s82, 0x100
	s_addc_u32 s83, s83, 0
	s_cmp_ge_u32 s2, s87
	s_mov_b32 s84, s2
	s_cbranch_scc0 .LBB0_724
	s_and_b64 vcc, exec, s[16:17]
	s_cbranch_vccz .LBB0_727
	s_barrier

; #define PG8_STAGE(bufoff, gbase, voff) do { _Pragma("unroll") for (int _i = 0; _i < 2; ++_i) \
;         __builtin_amdgcn_global_load_lds((const unsigned*)((const char*)(gbase) + (voff)[_i]), (PG8_LAS unsigned*)(lds + (bufoff) + ldsw + _i * 8192), 16, 0, 0); } while (0)
; #define PG8_LDA(dst, b, h) do { _Pragma("unroll") for (int m = 0; m < 4; ++m) _Pragma("unroll") for (int k = 0; k < 2; ++k) dst[m][k] = *(const PG8_LAS bf16x8*)(lds + PG8_SA(b, h) + aoff + m * 2048 + k * 1024); } while (0)
; #define PG8_LDB(dst, b, h) do { _Pragma("unroll") for (int n = 0; n < 2; ++n) _Pragma("unroll") for (int k = 0; k < 2; ++k) dst[n][k] = *(const PG8_LAS bf16x8*)(lds + PG8_SB(b, h) + boff + n * 2048 + k * 1024); } while (0)
; #define PG8_MMA(ai, bj, At, Bt) do { __builtin_amdgcn_s_setprio(1); _Pragma("unroll") for (int m = 0; m < 4; ++m) _Pragma("unroll") for (int n = 0; n < 2; ++n) _Pragma("unroll") for (int k = 0; k < 2; ++k) \
;         acc[ai][bj][m][n] = __builtin_amdgcn_mfma_f32_16x16x32_bf16(Bt[n][k], At[m][k], acc[ai][bj][m][n], 0, 0, 0); __builtin_amdgcn_s_setprio(0); } while (0)
; #define PG8_WAIT_V(n) asm volatile("s_waitcnt vmcnt(" #n ")" ::: "memory")
; #define PG8_WAIT_L(n) asm volatile("s_waitcnt lgkmcnt(" #n ")" ::: "memory")
; template <class Epi, class Sched, bool ALIGN_EPI = false, bool SP2 = false>
; __device__ __forceinline__ void gemm_phase(PG8_LAS unsigned char* lds, const Gemm g, const Sched& S, const Epi& E) {
;     ...
;             const bool last = (t == nt - 2);
;             const char* a1 = cA + (size_t)(t + 1) * kstep;
;             const char* a2 = last ? nA : cA + (size_t)(t + 2) * kstep; const char* b2 = last ? nB : cB + (size_t)(t + 2) * kstep;
;             const char* a3 = a2 + kstep; const char* b3 = b2 + kstep;
;             if (last && has_next) S.a_ready(nxt);
;             if constexpr (SP2) {
;             PG8_LDB(B0, 0, 0); PG8_LDB(B1, 0, 1); PG8_SCHED; PG8_LDA(At, 0, 0); PG8_STAGE(PG8_SA(1, 1), a1 + hstepA, voffA);
;             PG8_WAIT_V(8); PG8_WAIT_L(0); PG8_BAR; PG8_MMA(0, 0, At, B0); PG8_MMA(0, 1, At, B1); PG8_BAR; PG8_SCHED;
;             PG8_LDA(At, 0, 1); PG8_STAGE(PG8_SB(0, 0), b2, voffB); PG8_STAGE(PG8_SB(0, 1), b2 + hstepB, voffB); PG8_STAGE(PG8_SA(0, 0), a2, voffA);
;             PG8_WAIT_V(8); PG8_WAIT_L(0); PG8_BAR; PG8_MMA(1, 0, At, B0); PG8_MMA(1, 1, At, B1); PG8_BAR; PG8_SCHED;
.LBB0_766:
	s_add_i32 s2, s82, 2
	s_add_u32 s4, s66, 0x100
	s_addc_u32 s5, s67, 0
	s_add_i32 s3, 0, 0x10000
	s_cmp_eq_u32 s88, s82
	s_cselect_b32 s83, s15, s5
	s_cselect_b32 s82, s14, s4
	s_cselect_b32 s97, s17, s94
	s_cselect_b32 s96, s16, s93
	s_add_i32 s30, 0, 0x14000
	v_add_u32_e32 v140, s3, v222
	v_add_u32_e32 v156, s30, v222
	ds_read_b128 v[128:131], v140
	ds_read_b128 v[132:135], v140 offset:1024
	ds_read_b128 v[136:139], v140 offset:2048
	ds_read_b128 v[140:143], v140 offset:3072
	ds_read_b128 v[144:147], v156
	ds_read_b128 v[148:151], v156 offset:1024
	ds_read_b128 v[152:155], v156 offset:2048
	ds_read_b128 v[156:159], v156 offset:3072
	s_add_i32 m0, s62, 0xc000
	ds_read_b128 v[160:163], v223
	ds_read_b128 v[164:167], v223 offset:1024
	ds_read_b128 v[168:171], v223 offset:2048
	ds_read_b128 v[172:175], v223 offset:3072
	ds_read_b128 v[176:179], v223 offset:4096
	ds_read_b128 v[180:183], v223 offset:5120
	ds_read_b128 v[184:187], v223 offset:6144
	ds_read_b128 v[188:191], v223 offset:7168
	global_load_lds_dwordx4 v206, s[66:67]
	s_add_i32 m0, s62, 0xe000
	s_nop 0
	global_load_lds_dwordx4 v204, s[66:67]
	s_waitcnt vmcnt(8)
	s_waitcnt lgkmcnt(0)
	s_barrier
	s_setprio 1
	s_waitcnt lgkmcnt(0)
	v_mfma_f32_16x16x32_bf16 v[124:127], v[128:131], v[160:163], v[124:127]
	v_mfma_f32_16x16x32_bf16 v[120:123], v[136:139], v[160:163], v[120:123]
	v_mfma_f32_16x16x32_bf16 v[112:115], v[128:131], v[168:171], v[112:115]
	v_mfma_f32_16x16x32_bf16 v[104:107], v[136:139], v[168:171], v[104:107]
	v_mfma_f32_16x16x32_bf16 v[96:99], v[128:131], v[176:179], v[96:99]
	v_mfma_f32_16x16x32_bf16 v[88:91], v[136:139], v[176:179], v[88:91]
	v_mfma_f32_16x16x32_bf16 v[80:83], v[128:131], v[184:187], v[80:83]
	v_mfma_f32_16x16x32_bf16 v[72:75], v[136:139], v[184:187], v[72:75]
	v_mfma_f32_16x16x32_bf16 v[124:127], v[132:135], v[164:167], v[124:127]
	v_mfma_f32_16x16x32_bf16 v[120:123], v[140:143], v[164:167], v[120:123]
	v_mfma_f32_16x16x32_bf16 v[112:115], v[132:135], v[172:175], v[112:115]
	v_mfma_f32_16x16x32_bf16 v[104:107], v[140:143], v[172:175], v[104:107]
	v_mfma_f32_16x16x32_bf16 v[96:99], v[132:135], v[180:183], v[96:99]
	v_mfma_f32_16x16x32_bf16 v[88:91], v[140:143], v[180:183], v[88:91]
	v_mfma_f32_16x16x32_bf16 v[80:83], v[132:135], v[188:191], v[80:83]
	v_mfma_f32_16x16x32_bf16 v[72:75], v[140:143], v[188:191], v[72:75]
	s_setprio 0
	s_setprio 1
	v_mfma_f32_16x16x32_bf16 v[116:119], v[144:147], v[160:163], v[116:119]
	v_mfma_f32_16x16x32_bf16 v[108:111], v[152:155], v[160:163], v[108:111]
	v_mfma_f32_16x16x32_bf16 v[100:103], v[144:147], v[168:171], v[100:103]
	v_mfma_f32_16x16x32_bf16 v[92:95], v[152:155], v[168:171], v[92:95]
	v_mfma_f32_16x16x32_bf16 v[84:87], v[144:147], v[176:179], v[84:87]
	v_mfma_f32_16x16x32_bf16 v[76:79], v[152:155], v[176:179], v[76:79]
	v_mfma_f32_16x16x32_bf16 v[68:71], v[144:147], v[184:187], v[68:71]
	v_mfma_f32_16x16x32_bf16 v[64:67], v[152:155], v[184:187], v[64:67]
	v_mfma_f32_16x16x32_bf16 v[116:119], v[148:151], v[164:167], v[116:119]
	v_mfma_f32_16x16x32_bf16 v[108:111], v[156:159], v[164:167], v[108:111]
	v_mfma_f32_16x16x32_bf16 v[100:103], v[148:151], v[172:175], v[100:103]
	v_mfma_f32_16x16x32_bf16 v[92:95], v[156:159], v[172:175], v[92:95]
	v_mfma_f32_16x16x32_bf16 v[84:87], v[148:151], v[180:183], v[84:87]
	v_mfma_f32_16x16x32_bf16 v[76:79], v[156:159], v[180:183], v[76:79]
	v_mfma_f32_16x16x32_bf16 v[68:71], v[148:151], v[188:191], v[68:71]
	v_mfma_f32_16x16x32_bf16 v[64:67], v[156:159], v[188:191], v[64:67]
	s_setprio 0
	s_barrier
	s_add_i32 s3, s3, s49
	s_mov_b32 m0, s3
	ds_read_b128 v[160:163], v223 offset:16384
	ds_read_b128 v[164:167], v223 offset:17408
	ds_read_b128 v[168:171], v223 offset:18432
	ds_read_b128 v[172:175], v223 offset:19456
	ds_read_b128 v[176:179], v223 offset:20480
	ds_read_b128 v[180:183], v223 offset:21504
	ds_read_b128 v[184:187], v223 offset:22528
	ds_read_b128 v[188:191], v223 offset:23552
	global_load_lds_dwordx4 v192, s[96:97]
	s_add_i32 m0, s3, 0x2000
	s_add_u32 s66, s96, s34
	s_addc_u32 s67, s97, 0
	s_add_i32 s3, s30, s49
	global_load_lds_dwordx4 v198, s[96:97]
	v_lshl_add_u64 v[212:213], s[66:67], 0, v[192:193]
	s_mov_b32 m0, s3
	v_lshl_add_u64 v[214:215], s[66:67], 0, v[198:199]
	global_load_lds_dwordx4 v192, s[66:67]
	s_add_i32 m0, s3, 0x2000
	s_nop 0
	global_load_lds_dwordx4 v198, s[66:67]
	s_mov_b32 m0, s62
	s_nop 0
	global_load_lds_dwordx4 v202, s[82:83]
	s_mov_b32 m0, s63
	s_nop 0
	global_load_lds_dwordx4 v200, s[82:83]
	s_waitcnt vmcnt(8)
	s_waitcnt lgkmcnt(0)
	s_barrier
; #define PG8_STAGE(bufoff, gbase, voff) do { _Pragma("unroll") for (int _i = 0; _i < 2; ++_i) \
;         __builtin_amdgcn_global_load_lds((const unsigned*)((const char*)(gbase) + (voff)[_i]), (PG8_LAS unsigned*)(lds + (bufoff) + ldsw + _i * 8192), 16, 0, 0); } while (0)
; #define PG8_LDA(dst, b, h) do { _Pragma("unroll") for (int m = 0; m < 4; ++m) _Pragma("unroll") for (int k = 0; k < 2; ++k) dst[m][k] = *(const PG8_LAS bf16x8*)(lds + PG8_SA(b, h) + aoff + m * 2048 + k * 1024); } while (0)
; #define PG8_LDB(dst, b, h) do { _Pragma("unroll") for (int n = 0; n < 2; ++n) _Pragma("unroll") for (int k = 0; k < 2; ++k) dst[n][k] = *(const PG8_LAS bf16x8*)(lds + PG8_SB(b, h) + boff + n * 2048 + k * 1024); } while (0)
; #define PG8_MMA(ai, bj, At, Bt) do { __builtin_amdgcn_s_setprio(1); _Pragma("unroll") for (int m = 0; m < 4; ++m) _Pragma("unroll") for (int n = 0; n < 2; ++n) _Pragma("unroll") for (int k = 0; k < 2; ++k) \
;         acc[ai][bj][m][n] = __builtin_amdgcn_mfma_f32_16x16x32_bf16(Bt[n][k], At[m][k], acc[ai][bj][m][n], 0, 0, 0); __builtin_amdgcn_s_setprio(0); } while (0)
; #define PG8_WAIT_V(n) asm volatile("s_waitcnt vmcnt(" #n ")" ::: "memory")
; #define PG8_WAIT_L(n) asm volatile("s_waitcnt lgkmcnt(" #n ")" ::: "memory")
; #define PG8_BAR __builtin_amdgcn_s_barrier()
; #define PG8_SCHED __builtin_amdgcn_sched_barrier(0)
; template <class Epi, class Sched, bool ALIGN_EPI = false, bool SP2 = false>
; __device__ __forceinline__ void gemm_phase(PG8_LAS unsigned char* lds, const Gemm g, const Sched& S, const Epi& E) {
;     ...
;             PG8_WAIT_V(8); PG8_WAIT_L(0); PG8_BAR; PG8_MMA(1, 0, At, B0); PG8_MMA(1, 1, At, B1); PG8_BAR; PG8_SCHED;
;             PG8_LDB(B0, 1, 0); PG8_LDB(B1, 1, 1); PG8_SCHED; PG8_LDA(At, 1, 0); PG8_STAGE(PG8_SA(0, 1), a2 + hstepA, voffA);
;             PG8_WAIT_V(8); PG8_WAIT_L(0); PG8_BAR; PG8_MMA(0, 0, At, B0); PG8_MMA(0, 1, At, B1); PG8_BAR; PG8_SCHED;
	s_setprio 1
	s_waitcnt lgkmcnt(0)
	v_mfma_f32_16x16x32_bf16 v[60:63], v[128:131], v[160:163], v[60:63]
	v_mfma_f32_16x16x32_bf16 v[56:59], v[136:139], v[160:163], v[56:59]
	v_mfma_f32_16x16x32_bf16 v[48:51], v[128:131], v[168:171], v[48:51]
	v_mfma_f32_16x16x32_bf16 v[40:43], v[136:139], v[168:171], v[40:43]
	v_mfma_f32_16x16x32_bf16 v[32:35], v[128:131], v[176:179], v[32:35]
	v_mfma_f32_16x16x32_bf16 v[24:27], v[136:139], v[176:179], v[24:27]
	v_mfma_f32_16x16x32_bf16 v[16:19], v[128:131], v[184:187], v[16:19]
	v_mfma_f32_16x16x32_bf16 v[8:11], v[136:139], v[184:187], v[8:11]
	v_mfma_f32_16x16x32_bf16 v[60:63], v[132:135], v[164:167], v[60:63]
	v_mfma_f32_16x16x32_bf16 v[56:59], v[140:143], v[164:167], v[56:59]
	v_mfma_f32_16x16x32_bf16 v[48:51], v[132:135], v[172:175], v[48:51]
	v_mfma_f32_16x16x32_bf16 v[40:43], v[140:143], v[172:175], v[40:43]
	v_mfma_f32_16x16x32_bf16 v[32:35], v[132:135], v[180:183], v[32:35]
	v_mfma_f32_16x16x32_bf16 v[24:27], v[140:143], v[180:183], v[24:27]
	v_mfma_f32_16x16x32_bf16 v[16:19], v[132:135], v[188:191], v[16:19]
	v_mfma_f32_16x16x32_bf16 v[8:11], v[140:143], v[188:191], v[8:11]
	s_setprio 0
	s_setprio 1
	v_mfma_f32_16x16x32_bf16 v[52:55], v[144:147], v[160:163], v[52:55]
	v_mfma_f32_16x16x32_bf16 v[44:47], v[152:155], v[160:163], v[44:47]
	v_mfma_f32_16x16x32_bf16 v[36:39], v[144:147], v[168:171], v[36:39]
	v_mfma_f32_16x16x32_bf16 v[28:31], v[152:155], v[168:171], v[28:31]
	v_mfma_f32_16x16x32_bf16 v[20:23], v[144:147], v[176:179], v[20:23]
	v_mfma_f32_16x16x32_bf16 v[12:15], v[152:155], v[176:179], v[12:15]
	v_mfma_f32_16x16x32_bf16 v[4:7], v[144:147], v[184:187], v[4:7]
	v_mfma_f32_16x16x32_bf16 v[0:3], v[152:155], v[184:187], v[0:3]
	v_mfma_f32_16x16x32_bf16 v[52:55], v[148:151], v[164:167], v[52:55]
	v_mfma_f32_16x16x32_bf16 v[44:47], v[156:159], v[164:167], v[44:47]
	v_mfma_f32_16x16x32_bf16 v[36:39], v[148:151], v[172:175], v[36:39]
	v_mfma_f32_16x16x32_bf16 v[28:31], v[156:159], v[172:175], v[28:31]
	v_mfma_f32_16x16x32_bf16 v[20:23], v[148:151], v[180:183], v[20:23]
	v_mfma_f32_16x16x32_bf16 v[12:15], v[156:159], v[180:183], v[12:15]
	v_mfma_f32_16x16x32_bf16 v[4:7], v[148:151], v[188:191], v[4:7]
	v_mfma_f32_16x16x32_bf16 v[0:3], v[156:159], v[188:191], v[0:3]
	s_setprio 0
	s_barrier
	s_add_i32 s3, 0, 0x18000
	s_add_i32 s30, 0, 0x1c000
	v_add_u32_e32 v140, s3, v222
	v_add_u32_e32 v156, s30, v222
	ds_read_b128 v[128:131], v140
	ds_read_b128 v[132:135], v140 offset:1024
	ds_read_b128 v[136:139], v140 offset:2048
	ds_read_b128 v[140:143], v140 offset:3072
	ds_read_b128 v[144:147], v156
	ds_read_b128 v[148:151], v156 offset:1024
	ds_read_b128 v[152:155], v156 offset:2048
	ds_read_b128 v[156:159], v156 offset:3072
	s_add_u32 s66, s82, 0x130000
	s_addc_u32 s67, s83, 0
	s_mov_b32 m0, s64
	ds_read_b128 v[160:163], v223 offset:32768
	ds_read_b128 v[164:167], v223 offset:33792
	ds_read_b128 v[168:171], v223 offset:34816
	ds_read_b128 v[172:175], v223 offset:35840
	ds_read_b128 v[176:179], v223 offset:36864
	ds_read_b128 v[180:183], v223 offset:37888
	ds_read_b128 v[184:187], v223 offset:38912
	ds_read_b128 v[188:191], v223 offset:39936
	global_load_lds_dwordx4 v202, s[66:67]
	s_mov_b32 m0, s65
	s_nop 0
	global_load_lds_dwordx4 v200, s[66:67]
	s_waitcnt vmcnt(8)
	s_waitcnt lgkmcnt(0)
	s_barrier
	s_setprio 1
	s_waitcnt lgkmcnt(0)
	v_mfma_f32_16x16x32_bf16 v[124:127], v[128:131], v[160:163], v[124:127]
	v_mfma_f32_16x16x32_bf16 v[120:123], v[136:139], v[160:163], v[120:123]
	v_mfma_f32_16x16x32_bf16 v[112:115], v[128:131], v[168:171], v[112:115]
	v_mfma_f32_16x16x32_bf16 v[104:107], v[136:139], v[168:171], v[104:107]
	v_mfma_f32_16x16x32_bf16 v[96:99], v[128:131], v[176:179], v[96:99]
	v_mfma_f32_16x16x32_bf16 v[88:91], v[136:139], v[176:179], v[88:91]
	v_mfma_f32_16x16x32_bf16 v[80:83], v[128:131], v[184:187], v[80:83]
	v_mfma_f32_16x16x32_bf16 v[72:75], v[136:139], v[184:187], v[72:75]
	v_mfma_f32_16x16x32_bf16 v[124:127], v[132:135], v[164:167], v[124:127]
	v_mfma_f32_16x16x32_bf16 v[120:123], v[140:143], v[164:167], v[120:123]
	v_mfma_f32_16x16x32_bf16 v[112:115], v[132:135], v[172:175], v[112:115]
	v_mfma_f32_16x16x32_bf16 v[104:107], v[140:143], v[172:175], v[104:107]
	v_mfma_f32_16x16x32_bf16 v[96:99], v[132:135], v[180:183], v[96:99]
	v_mfma_f32_16x16x32_bf16 v[88:91], v[140:143], v[180:183], v[88:91]
	v_mfma_f32_16x16x32_bf16 v[80:83], v[132:135], v[188:191], v[80:83]
	v_mfma_f32_16x16x32_bf16 v[72:75], v[140:143], v[188:191], v[72:75]
	s_setprio 0
	s_setprio 1
	v_mfma_f32_16x16x32_bf16 v[116:119], v[144:147], v[160:163], v[116:119]
	v_mfma_f32_16x16x32_bf16 v[108:111], v[152:155], v[160:163], v[108:111]
	v_mfma_f32_16x16x32_bf16 v[100:103], v[144:147], v[168:171], v[100:103]
	v_mfma_f32_16x16x32_bf16 v[92:95], v[152:155], v[168:171], v[92:95]
	v_mfma_f32_16x16x32_bf16 v[84:87], v[144:147], v[176:179], v[84:87]
	v_mfma_f32_16x16x32_bf16 v[76:79], v[152:155], v[176:179], v[76:79]
	v_mfma_f32_16x16x32_bf16 v[68:71], v[144:147], v[184:187], v[68:71]
	v_mfma_f32_16x16x32_bf16 v[64:67], v[152:155], v[184:187], v[64:67]
	v_mfma_f32_16x16x32_bf16 v[116:119], v[148:151], v[164:167], v[116:119]
	v_mfma_f32_16x16x32_bf16 v[108:111], v[156:159], v[164:167], v[108:111]
	v_mfma_f32_16x16x32_bf16 v[100:103], v[148:151], v[172:175], v[100:103]
	v_mfma_f32_16x16x32_bf16 v[92:95], v[156:159], v[172:175], v[92:95]
	v_mfma_f32_16x16x32_bf16 v[84:87], v[148:151], v[180:183], v[84:87]
	v_mfma_f32_16x16x32_bf16 v[76:79], v[156:159], v[180:183], v[76:79]
	v_mfma_f32_16x16x32_bf16 v[68:71], v[148:151], v[188:191], v[68:71]
	v_mfma_f32_16x16x32_bf16 v[64:67], v[156:159], v[188:191], v[64:67]
	s_setprio 0
	s_barrier
; #define PG8_STAGE(bufoff, gbase, voff) do { _Pragma("unroll") for (int _i = 0; _i < 2; ++_i) \
;         __builtin_amdgcn_global_load_lds((const unsigned*)((const char*)(gbase) + (voff)[_i]), (PG8_LAS unsigned*)(lds + (bufoff) + ldsw + _i * 8192), 16, 0, 0); } while (0)
; #define PG8_LDA(dst, b, h) do { _Pragma("unroll") for (int m = 0; m < 4; ++m) _Pragma("unroll") for (int k = 0; k < 2; ++k) dst[m][k] = *(const PG8_LAS bf16x8*)(lds + PG8_SA(b, h) + aoff + m * 2048 + k * 1024); } while (0)
; #define PG8_MMA(ai, bj, At, Bt) do { __builtin_amdgcn_s_setprio(1); _Pragma("unroll") for (int m = 0; m < 4; ++m) _Pragma("unroll") for (int n = 0; n < 2; ++n) _Pragma("unroll") for (int k = 0; k < 2; ++k) \
;         acc[ai][bj][m][n] = __builtin_amdgcn_mfma_f32_16x16x32_bf16(Bt[n][k], At[m][k], acc[ai][bj][m][n], 0, 0, 0); __builtin_amdgcn_s_setprio(0); } while (0)
; #define PG8_WAIT_V(n) asm volatile("s_waitcnt vmcnt(" #n ")" ::: "memory")
; #define PG8_WAIT_L(n) asm volatile("s_waitcnt lgkmcnt(" #n ")" ::: "memory")
; #define PG8_BAR __builtin_amdgcn_s_barrier()
; #define PG8_SCHED __builtin_amdgcn_sched_barrier(0)
; template <class Epi, class Sched, bool ALIGN_EPI = false, bool SP2 = false>
; __device__ __forceinline__ void gemm_phase(PG8_LAS unsigned char* lds, const Gemm g, const Sched& S, const Epi& E) {
;     ...
;             PG8_LDA(At, 1, 1); PG8_STAGE(PG8_SB(1, 0), b3, voffB); PG8_STAGE(PG8_SB(1, 1), b3 + hstepB, voffB); PG8_STAGE(PG8_SA(1, 0), a3, voffA);
;             PG8_WAIT_V(8); PG8_WAIT_L(0); PG8_BAR; PG8_MMA(1, 0, At, B0); PG8_MMA(1, 1, At, B1); PG8_BAR; PG8_SCHED;
	s_add_i32 s3, s3, s49
	s_add_i32 m0, s3, 0xffffff80
	ds_read_b128 v[160:163], v223 offset:49152
	ds_read_b128 v[164:167], v223 offset:50176
	ds_read_b128 v[168:171], v223 offset:51200
	ds_read_b128 v[172:175], v223 offset:52224
	ds_read_b128 v[176:179], v223 offset:53248
	ds_read_b128 v[180:183], v223 offset:54272
	ds_read_b128 v[184:187], v223 offset:55296
	ds_read_b128 v[188:191], v223 offset:56320
	global_load_lds_dwordx4 v192, s[96:97] offset:128
	s_add_i32 m0, s3, 0x1f80
	s_add_i32 s3, s30, s49
	global_load_lds_dwordx4 v198, s[96:97] offset:128
	v_lshl_add_u64 v[208:209], v[212:213], 0, s[36:37]
	s_mov_b32 m0, s3
	s_nop 0
	global_load_lds_dwordx4 v[208:209], off
	v_lshl_add_u64 v[208:209], v[214:215], 0, s[36:37]
	s_add_i32 m0, s3, 0x2000
	s_nop 0
	global_load_lds_dwordx4 v[208:209], off
	s_add_i32 m0, s86, 0xffffff80
	s_nop 0
	global_load_lds_dwordx4 v202, s[82:83] offset:128
	s_add_i32 m0, s87, 0xffffff80
	s_nop 0
	global_load_lds_dwordx4 v200, s[82:83] offset:128
	s_waitcnt vmcnt(8)
	s_waitcnt lgkmcnt(0)
	s_barrier
	s_setprio 1
	s_waitcnt lgkmcnt(0)
	v_mfma_f32_16x16x32_bf16 v[60:63], v[128:131], v[160:163], v[60:63]
	v_mfma_f32_16x16x32_bf16 v[56:59], v[136:139], v[160:163], v[56:59]
	v_mfma_f32_16x16x32_bf16 v[48:51], v[128:131], v[168:171], v[48:51]
	v_mfma_f32_16x16x32_bf16 v[40:43], v[136:139], v[168:171], v[40:43]
	v_mfma_f32_16x16x32_bf16 v[32:35], v[128:131], v[176:179], v[32:35]
	v_mfma_f32_16x16x32_bf16 v[24:27], v[136:139], v[176:179], v[24:27]
	v_mfma_f32_16x16x32_bf16 v[16:19], v[128:131], v[184:187], v[16:19]
	v_mfma_f32_16x16x32_bf16 v[8:11], v[136:139], v[184:187], v[8:11]
	v_mfma_f32_16x16x32_bf16 v[60:63], v[132:135], v[164:167], v[60:63]
	v_mfma_f32_16x16x32_bf16 v[56:59], v[140:143], v[164:167], v[56:59]
	v_mfma_f32_16x16x32_bf16 v[48:51], v[132:135], v[172:175], v[48:51]
	v_mfma_f32_16x16x32_bf16 v[40:43], v[140:143], v[172:175], v[40:43]
	v_mfma_f32_16x16x32_bf16 v[32:35], v[132:135], v[180:183], v[32:35]
	v_mfma_f32_16x16x32_bf16 v[24:27], v[140:143], v[180:183], v[24:27]
	v_mfma_f32_16x16x32_bf16 v[16:19], v[132:135], v[188:191], v[16:19]
	v_mfma_f32_16x16x32_bf16 v[8:11], v[140:143], v[188:191], v[8:11]
	s_setprio 0
	s_setprio 1
	v_mfma_f32_16x16x32_bf16 v[52:55], v[144:147], v[160:163], v[52:55]
	v_mfma_f32_16x16x32_bf16 v[44:47], v[152:155], v[160:163], v[44:47]
	v_mfma_f32_16x16x32_bf16 v[36:39], v[144:147], v[168:171], v[36:39]
	v_mfma_f32_16x16x32_bf16 v[28:31], v[152:155], v[168:171], v[28:31]
	v_mfma_f32_16x16x32_bf16 v[20:23], v[144:147], v[176:179], v[20:23]
	v_mfma_f32_16x16x32_bf16 v[12:15], v[152:155], v[176:179], v[12:15]
	v_mfma_f32_16x16x32_bf16 v[4:7], v[144:147], v[184:187], v[4:7]
	v_mfma_f32_16x16x32_bf16 v[0:3], v[152:155], v[184:187], v[0:3]
	v_mfma_f32_16x16x32_bf16 v[52:55], v[148:151], v[164:167], v[52:55]
	v_mfma_f32_16x16x32_bf16 v[44:47], v[156:159], v[164:167], v[44:47]
	v_mfma_f32_16x16x32_bf16 v[36:39], v[148:151], v[172:175], v[36:39]
	v_mfma_f32_16x16x32_bf16 v[28:31], v[156:159], v[172:175], v[28:31]
	v_mfma_f32_16x16x32_bf16 v[20:23], v[148:151], v[180:183], v[20:23]
	v_mfma_f32_16x16x32_bf16 v[12:15], v[156:159], v[180:183], v[12:15]
	v_mfma_f32_16x16x32_bf16 v[4:7], v[148:151], v[188:191], v[4:7]
	v_mfma_f32_16x16x32_bf16 v[0:3], v[156:159], v[188:191], v[0:3]
	s_setprio 0
	s_barrier
	s_add_u32 s93, s93, 0x100
	s_addc_u32 s94, s94, 0
	s_cmp_ge_u32 s2, s80
	s_mov_b64 s[66:67], s[4:5]
	s_mov_b32 s82, s2
	s_cbranch_scc0 .LBB0_766
	s_and_b64 vcc, exec, s[12:13]
	s_cbranch_vccz .LBB0_769
	s_barrier

; #define PG8_STAGE(bufoff, gbase, voff) do { _Pragma("unroll") for (int _i = 0; _i < 2; ++_i) \
;         __builtin_amdgcn_global_load_lds((const unsigned*)((const char*)(gbase) + (voff)[_i]), (PG8_LAS unsigned*)(lds + (bufoff) + ldsw + _i * 8192), 16, 0, 0); } while (0)
; #define PG8_LDA(dst, b, h) do { _Pragma("unroll") for (int m = 0; m < 4; ++m) _Pragma("unroll") for (int k = 0; k < 2; ++k) dst[m][k] = *(const PG8_LAS bf16x8*)(lds + PG8_SA(b, h) + aoff + m * 2048 + k * 1024); } while (0)
; #define PG8_LDB(dst, b, h) do { _Pragma("unroll") for (int n = 0; n < 2; ++n) _Pragma("unroll") for (int k = 0; k < 2; ++k) dst[n][k] = *(const PG8_LAS bf16x8*)(lds + PG8_SB(b, h) + boff + n * 2048 + k * 1024); } while (0)
; #define PG8_MMA(ai, bj, At, Bt) do { __builtin_amdgcn_s_setprio(1); _Pragma("unroll") for (int m = 0; m < 4; ++m) _Pragma("unroll") for (int n = 0; n < 2; ++n) _Pragma("unroll") for (int k = 0; k < 2; ++k) \
;         acc[ai][bj][m][n] = __builtin_amdgcn_mfma_f32_16x16x32_bf16(Bt[n][k], At[m][k], acc[ai][bj][m][n], 0, 0, 0); __builtin_amdgcn_s_setprio(0); } while (0)
; #define PG8_WAIT_V(n) asm volatile("s_waitcnt vmcnt(" #n ")" ::: "memory")
; #define PG8_WAIT_L(n) asm volatile("s_waitcnt lgkmcnt(" #n ")" ::: "memory")
; template <class Epi, class Sched, bool ALIGN_EPI = false, bool SP2 = false>
; __device__ __forceinline__ void gemm_phase(PG8_LAS unsigned char* lds, const Gemm g, const Sched& S, const Epi& E) {
;     ...
;             const bool last = (t == nt - 2);
;             const char* a1 = cA + (size_t)(t + 1) * kstep;
;             const char* a2 = last ? nA : cA + (size_t)(t + 2) * kstep; const char* b2 = last ? nB : cB + (size_t)(t + 2) * kstep;
;             const char* a3 = a2 + kstep; const char* b3 = b2 + kstep;
;             if (last && has_next) S.a_ready(nxt);
;             if constexpr (SP2) {
;             PG8_LDB(B0, 0, 0); PG8_LDB(B1, 0, 1); PG8_SCHED; PG8_LDA(At, 0, 0); PG8_STAGE(PG8_SA(1, 1), a1 + hstepA, voffA);
;             PG8_WAIT_V(8); PG8_WAIT_L(0); PG8_BAR; PG8_MMA(0, 0, At, B0); PG8_MMA(0, 1, At, B1); PG8_BAR; PG8_SCHED;
;             PG8_LDA(At, 0, 1); PG8_STAGE(PG8_SB(0, 0), b2, voffB); PG8_STAGE(PG8_SB(0, 1), b2 + hstepB, voffB); PG8_STAGE(PG8_SA(0, 0), a2, voffA);
;             PG8_WAIT_V(8); PG8_WAIT_L(0); PG8_BAR; PG8_MMA(1, 0, At, B0); PG8_MMA(1, 1, At, B1); PG8_BAR; PG8_SCHED;
.LBB0_817:
	s_add_u32 s2, s0, 0xfffc0080
	s_addc_u32 s3, s1, -1
	s_add_i32 s30, 0, 0x10000
	s_cmp_eq_u32 s78, 12
	s_cselect_b32 s11, s7, s3
	s_cselect_b32 s10, s12, s2
	s_cselect_b32 s9, s13, s17
	s_cselect_b32 s8, s15, s16
	s_add_i32 s31, 0, 0x14000
	v_add_u32_e32 v84, s30, v240
	v_add_u32_e32 v116, s31, v240
	ds_read_b128 v[72:75], v84
	ds_read_b128 v[76:79], v84 offset:1024
	ds_read_b128 v[80:83], v84 offset:2048
	ds_read_b128 v[84:87], v84 offset:3072
	ds_read_b128 v[104:107], v116
	ds_read_b128 v[108:111], v116 offset:1024
	ds_read_b128 v[112:115], v116 offset:2048
	ds_read_b128 v[116:119], v116 offset:3072
	s_add_i32 m0, s19, 0xc000
	ds_read_b128 v[136:139], v241
	ds_read_b128 v[140:143], v241 offset:1024
	ds_read_b128 v[144:147], v241 offset:2048
	ds_read_b128 v[148:151], v241 offset:3072
	ds_read_b128 v[168:171], v241 offset:4096
	ds_read_b128 v[172:175], v241 offset:5120
	ds_read_b128 v[176:179], v241 offset:6144
	ds_read_b128 v[180:183], v241 offset:7168
	global_load_lds_dwordx4 v206, s[0:1]
	s_add_i32 m0, s19, 0xe000
	s_nop 0
	global_load_lds_dwordx4 v204, s[0:1]
	s_waitcnt vmcnt(8)
	s_waitcnt lgkmcnt(0)
	s_barrier
	s_setprio 1
	s_waitcnt lgkmcnt(0)
	v_mfma_f32_16x16x32_bf16 v[188:191], v[72:75], v[136:139], v[188:191]
	v_mfma_f32_16x16x32_bf16 v[184:187], v[80:83], v[136:139], v[184:187]
	v_mfma_f32_16x16x32_bf16 v[156:159], v[72:75], v[144:147], v[156:159]
	v_mfma_f32_16x16x32_bf16 v[152:155], v[80:83], v[144:147], v[152:155]
	v_mfma_f32_16x16x32_bf16 v[124:127], v[72:75], v[168:171], v[124:127]
	v_mfma_f32_16x16x32_bf16 v[120:123], v[80:83], v[168:171], v[120:123]
	v_mfma_f32_16x16x32_bf16 v[92:95], v[72:75], v[176:179], v[92:95]
	v_mfma_f32_16x16x32_bf16 v[88:91], v[80:83], v[176:179], v[88:91]
	v_mfma_f32_16x16x32_bf16 v[188:191], v[76:79], v[140:143], v[188:191]
	v_mfma_f32_16x16x32_bf16 v[184:187], v[84:87], v[140:143], v[184:187]
	v_mfma_f32_16x16x32_bf16 v[156:159], v[76:79], v[148:151], v[156:159]
	v_mfma_f32_16x16x32_bf16 v[152:155], v[84:87], v[148:151], v[152:155]
	v_mfma_f32_16x16x32_bf16 v[124:127], v[76:79], v[172:175], v[124:127]
	v_mfma_f32_16x16x32_bf16 v[120:123], v[84:87], v[172:175], v[120:123]
	v_mfma_f32_16x16x32_bf16 v[92:95], v[76:79], v[180:183], v[92:95]
	v_mfma_f32_16x16x32_bf16 v[88:91], v[84:87], v[180:183], v[88:91]
	s_setprio 0
	s_setprio 1
	v_mfma_f32_16x16x32_bf16 v[164:167], v[104:107], v[136:139], v[164:167]
	v_mfma_f32_16x16x32_bf16 v[132:135], v[104:107], v[144:147], v[132:135]
	v_mfma_f32_16x16x32_bf16 v[128:131], v[112:115], v[144:147], v[128:131]
	v_mfma_f32_16x16x32_bf16 v[100:103], v[104:107], v[168:171], v[100:103]
	v_mfma_f32_16x16x32_bf16 v[96:99], v[112:115], v[168:171], v[96:99]
	v_mfma_f32_16x16x32_bf16 v[68:71], v[104:107], v[176:179], v[68:71]
	v_mfma_f32_16x16x32_bf16 v[64:67], v[112:115], v[176:179], v[64:67]
	v_mfma_f32_16x16x32_bf16 v[164:167], v[108:111], v[140:143], v[164:167]
	v_mfma_f32_16x16x32_bf16 v[136:139], v[112:115], v[136:139], v[160:163]
	v_mfma_f32_16x16x32_bf16 v[132:135], v[108:111], v[148:151], v[132:135]
	v_mfma_f32_16x16x32_bf16 v[128:131], v[116:119], v[148:151], v[128:131]
	v_mfma_f32_16x16x32_bf16 v[100:103], v[108:111], v[172:175], v[100:103]
	v_mfma_f32_16x16x32_bf16 v[96:99], v[116:119], v[172:175], v[96:99]
	v_mfma_f32_16x16x32_bf16 v[68:71], v[108:111], v[180:183], v[68:71]
	v_mfma_f32_16x16x32_bf16 v[64:67], v[116:119], v[180:183], v[64:67]
	v_mfma_f32_16x16x32_bf16 v[136:139], v[116:119], v[140:143], v[136:139]
	s_setprio 0
	s_barrier
	s_add_i32 s2, s30, s18
	s_mov_b32 m0, s2
	ds_read_b128 v[140:143], v241 offset:16384
	ds_read_b128 v[144:147], v241 offset:17408
	ds_read_b128 v[148:151], v241 offset:18432
	ds_read_b128 v[160:163], v241 offset:19456
	ds_read_b128 v[168:171], v241 offset:20480
	ds_read_b128 v[172:175], v241 offset:21504
	ds_read_b128 v[176:179], v241 offset:22528
	ds_read_b128 v[180:183], v241 offset:23552
	global_load_lds_dwordx4 v192, s[8:9]
	s_add_i32 m0, s2, 0x2000
	s_add_u32 s2, s8, 0x40000
	s_addc_u32 s3, s9, 0
	s_add_i32 s30, s31, s18
	global_load_lds_dwordx4 v202, s[8:9]
	s_mov_b32 m0, s30
	s_nop 0
	global_load_lds_dwordx4 v192, s[2:3]
	s_add_i32 m0, s30, 0x2000
	s_nop 0
	global_load_lds_dwordx4 v202, s[2:3]
	s_mov_b32 m0, s19
	s_nop 0
	global_load_lds_dwordx4 v198, s[10:11]
	s_mov_b32 m0, s45
	s_nop 0
	global_load_lds_dwordx4 v200, s[10:11]
	s_waitcnt vmcnt(8)
	s_waitcnt lgkmcnt(0)
	s_barrier
	s_setprio 1
	s_waitcnt lgkmcnt(0)
	v_mfma_f32_16x16x32_bf16 v[60:63], v[72:75], v[140:143], v[60:63]
	v_mfma_f32_16x16x32_bf16 v[56:59], v[80:83], v[140:143], v[56:59]
	v_mfma_f32_16x16x32_bf16 v[44:47], v[72:75], v[148:151], v[44:47]
	v_mfma_f32_16x16x32_bf16 v[40:43], v[80:83], v[148:151], v[40:43]
	v_mfma_f32_16x16x32_bf16 v[28:31], v[72:75], v[168:171], v[28:31]
	v_mfma_f32_16x16x32_bf16 v[24:27], v[80:83], v[168:171], v[24:27]
	v_mfma_f32_16x16x32_bf16 v[12:15], v[72:75], v[176:179], v[12:15]
	v_mfma_f32_16x16x32_bf16 v[8:11], v[80:83], v[176:179], v[8:11]
	v_mfma_f32_16x16x32_bf16 v[60:63], v[76:79], v[144:147], v[60:63]
	v_mfma_f32_16x16x32_bf16 v[56:59], v[84:87], v[144:147], v[56:59]
	v_mfma_f32_16x16x32_bf16 v[44:47], v[76:79], v[160:163], v[44:47]
	v_mfma_f32_16x16x32_bf16 v[40:43], v[84:87], v[160:163], v[40:43]
	v_mfma_f32_16x16x32_bf16 v[28:31], v[76:79], v[172:175], v[28:31]
	v_mfma_f32_16x16x32_bf16 v[24:27], v[84:87], v[172:175], v[24:27]
	v_mfma_f32_16x16x32_bf16 v[12:15], v[76:79], v[180:183], v[12:15]
	v_mfma_f32_16x16x32_bf16 v[8:11], v[84:87], v[180:183], v[8:11]
	s_setprio 0
	s_setprio 1
	v_mfma_f32_16x16x32_bf16 v[52:55], v[104:107], v[140:143], v[52:55]
	v_mfma_f32_16x16x32_bf16 v[48:51], v[112:115], v[140:143], v[48:51]
	v_mfma_f32_16x16x32_bf16 v[36:39], v[104:107], v[148:151], v[36:39]
	v_mfma_f32_16x16x32_bf16 v[32:35], v[112:115], v[148:151], v[32:35]
	v_mfma_f32_16x16x32_bf16 v[20:23], v[104:107], v[168:171], v[20:23]
	v_mfma_f32_16x16x32_bf16 v[16:19], v[112:115], v[168:171], v[16:19]
	v_mfma_f32_16x16x32_bf16 v[4:7], v[104:107], v[176:179], v[4:7]
	v_mfma_f32_16x16x32_bf16 v[0:3], v[112:115], v[176:179], v[0:3]
	v_mfma_f32_16x16x32_bf16 v[52:55], v[108:111], v[144:147], v[52:55]
	v_mfma_f32_16x16x32_bf16 v[48:51], v[116:119], v[144:147], v[48:51]
	v_mfma_f32_16x16x32_bf16 v[36:39], v[108:111], v[160:163], v[36:39]
	v_mfma_f32_16x16x32_bf16 v[32:35], v[116:119], v[160:163], v[32:35]
	v_mfma_f32_16x16x32_bf16 v[20:23], v[108:111], v[172:175], v[20:23]
	v_mfma_f32_16x16x32_bf16 v[16:19], v[116:119], v[172:175], v[16:19]
	v_mfma_f32_16x16x32_bf16 v[4:7], v[108:111], v[180:183], v[4:7]
	v_mfma_f32_16x16x32_bf16 v[0:3], v[116:119], v[180:183], v[0:3]
	s_setprio 0
	s_barrier
; #define PG8_STAGE(bufoff, gbase, voff) do { _Pragma("unroll") for (int _i = 0; _i < 2; ++_i) \
;         __builtin_amdgcn_global_load_lds((const unsigned*)((const char*)(gbase) + (voff)[_i]), (PG8_LAS unsigned*)(lds + (bufoff) + ldsw + _i * 8192), 16, 0, 0); } while (0)
; #define PG8_LDA(dst, b, h) do { _Pragma("unroll") for (int m = 0; m < 4; ++m) _Pragma("unroll") for (int k = 0; k < 2; ++k) dst[m][k] = *(const PG8_LAS bf16x8*)(lds + PG8_SA(b, h) + aoff + m * 2048 + k * 1024); } while (0)
; #define PG8_LDB(dst, b, h) do { _Pragma("unroll") for (int n = 0; n < 2; ++n) _Pragma("unroll") for (int k = 0; k < 2; ++k) dst[n][k] = *(const PG8_LAS bf16x8*)(lds + PG8_SB(b, h) + boff + n * 2048 + k * 1024); } while (0)
; #define PG8_MMA(ai, bj, At, Bt) do { __builtin_amdgcn_s_setprio(1); _Pragma("unroll") for (int m = 0; m < 4; ++m) _Pragma("unroll") for (int n = 0; n < 2; ++n) _Pragma("unroll") for (int k = 0; k < 2; ++k) \
;         acc[ai][bj][m][n] = __builtin_amdgcn_mfma_f32_16x16x32_bf16(Bt[n][k], At[m][k], acc[ai][bj][m][n], 0, 0, 0); __builtin_amdgcn_s_setprio(0); } while (0)
; #define PG8_WAIT_V(n) asm volatile("s_waitcnt vmcnt(" #n ")" ::: "memory")
; #define PG8_WAIT_L(n) asm volatile("s_waitcnt lgkmcnt(" #n ")" ::: "memory")
; #define PG8_BAR __builtin_amdgcn_s_barrier()
; #define PG8_SCHED __builtin_amdgcn_sched_barrier(0)
; template <class Epi, class Sched, bool ALIGN_EPI = false, bool SP2 = false>
; __device__ __forceinline__ void gemm_phase(PG8_LAS unsigned char* lds, const Gemm g, const Sched& S, const Epi& E) {
;     ...
;             PG8_LDB(B0, 1, 0); PG8_LDB(B1, 1, 1); PG8_SCHED; PG8_LDA(At, 1, 0); PG8_STAGE(PG8_SA(0, 1), a2 + hstepA, voffA);
;             PG8_WAIT_V(8); PG8_WAIT_L(0); PG8_BAR; PG8_MMA(0, 0, At, B0); PG8_MMA(0, 1, At, B1); PG8_BAR; PG8_SCHED;
;             PG8_LDA(At, 1, 1); PG8_STAGE(PG8_SB(1, 0), b3, voffB); PG8_STAGE(PG8_SB(1, 1), b3 + hstepB, voffB); PG8_STAGE(PG8_SA(1, 0), a3, voffA);
;             PG8_WAIT_V(8); PG8_WAIT_L(0); PG8_BAR; PG8_MMA(1, 0, At, B0); PG8_MMA(1, 1, At, B1); PG8_BAR; PG8_SCHED;
	s_add_i32 s30, 0, 0x18000
	s_add_i32 s31, 0, 0x1c000
	v_add_u32_e32 v84, s30, v240
	v_add_u32_e32 v116, s31, v240
	ds_read_b128 v[72:75], v84
	ds_read_b128 v[76:79], v84 offset:1024
	ds_read_b128 v[80:83], v84 offset:2048
	ds_read_b128 v[84:87], v84 offset:3072
	ds_read_b128 v[104:107], v116
	ds_read_b128 v[108:111], v116 offset:1024
	ds_read_b128 v[112:115], v116 offset:2048
	ds_read_b128 v[116:119], v116 offset:3072
	s_add_u32 s2, s10, 0x40000
	s_addc_u32 s3, s11, 0
	s_mov_b32 m0, s64
	ds_read_b128 v[140:143], v241 offset:32768
	ds_read_b128 v[144:147], v241 offset:33792
	ds_read_b128 v[148:151], v241 offset:34816
	ds_read_b128 v[168:171], v241 offset:35840
	ds_read_b128 v[172:175], v241 offset:36864
	ds_read_b128 v[176:179], v241 offset:37888
	ds_read_b128 v[180:183], v241 offset:38912
	ds_read_b128 v[208:211], v241 offset:39936
	global_load_lds_dwordx4 v198, s[2:3]
	s_mov_b32 m0, s65
	s_nop 0
	global_load_lds_dwordx4 v200, s[2:3]
	s_waitcnt vmcnt(8)
	s_waitcnt lgkmcnt(0)
	s_barrier
	s_setprio 1
	s_waitcnt lgkmcnt(0)
	v_mfma_f32_16x16x32_bf16 v[160:163], v[72:75], v[140:143], v[188:191]
	v_mfma_f32_16x16x32_bf16 v[188:191], v[76:79], v[144:147], v[160:163]
	v_mfma_f32_16x16x32_bf16 v[160:163], v[80:83], v[140:143], v[184:187]
	v_mfma_f32_16x16x32_bf16 v[156:159], v[72:75], v[148:151], v[156:159]
	v_mfma_f32_16x16x32_bf16 v[152:155], v[80:83], v[148:151], v[152:155]
	v_mfma_f32_16x16x32_bf16 v[124:127], v[72:75], v[172:175], v[124:127]
	v_mfma_f32_16x16x32_bf16 v[120:123], v[80:83], v[172:175], v[120:123]
	v_mfma_f32_16x16x32_bf16 v[92:95], v[72:75], v[180:183], v[92:95]
	v_mfma_f32_16x16x32_bf16 v[88:91], v[80:83], v[180:183], v[88:91]
	v_mfma_f32_16x16x32_bf16 v[184:187], v[84:87], v[144:147], v[160:163]
	v_mfma_f32_16x16x32_bf16 v[156:159], v[76:79], v[168:171], v[156:159]
	v_mfma_f32_16x16x32_bf16 v[152:155], v[84:87], v[168:171], v[152:155]
	v_mfma_f32_16x16x32_bf16 v[124:127], v[76:79], v[176:179], v[124:127]
	v_mfma_f32_16x16x32_bf16 v[120:123], v[84:87], v[176:179], v[120:123]
	v_mfma_f32_16x16x32_bf16 v[92:95], v[76:79], v[208:211], v[92:95]
	v_mfma_f32_16x16x32_bf16 v[88:91], v[84:87], v[208:211], v[88:91]
	s_setprio 0
	s_setprio 1
	v_mfma_f32_16x16x32_bf16 v[160:163], v[104:107], v[140:143], v[164:167]
	v_mfma_f32_16x16x32_bf16 v[136:139], v[112:115], v[140:143], v[136:139]
	v_mfma_f32_16x16x32_bf16 v[132:135], v[104:107], v[148:151], v[132:135]
	v_mfma_f32_16x16x32_bf16 v[128:131], v[112:115], v[148:151], v[128:131]
	v_mfma_f32_16x16x32_bf16 v[100:103], v[104:107], v[172:175], v[100:103]
	v_mfma_f32_16x16x32_bf16 v[96:99], v[112:115], v[172:175], v[96:99]
	v_mfma_f32_16x16x32_bf16 v[68:71], v[104:107], v[180:183], v[68:71]
	v_mfma_f32_16x16x32_bf16 v[64:67], v[112:115], v[180:183], v[64:67]
	v_mfma_f32_16x16x32_bf16 v[164:167], v[108:111], v[144:147], v[160:163]
	v_mfma_f32_16x16x32_bf16 v[160:163], v[116:119], v[144:147], v[136:139]
	v_mfma_f32_16x16x32_bf16 v[132:135], v[108:111], v[168:171], v[132:135]
	v_mfma_f32_16x16x32_bf16 v[128:131], v[116:119], v[168:171], v[128:131]
	v_mfma_f32_16x16x32_bf16 v[100:103], v[108:111], v[176:179], v[100:103]
	v_mfma_f32_16x16x32_bf16 v[96:99], v[116:119], v[176:179], v[96:99]
	v_mfma_f32_16x16x32_bf16 v[68:71], v[108:111], v[208:211], v[68:71]
	v_mfma_f32_16x16x32_bf16 v[64:67], v[116:119], v[208:211], v[64:67]
	s_setprio 0
	s_barrier
	s_add_i32 s2, s30, s18
	s_add_i32 m0, s2, 0xffffff80
	ds_read_b128 v[136:139], v241 offset:49152
	ds_read_b128 v[140:143], v241 offset:50176
	ds_read_b128 v[144:147], v241 offset:51200
	ds_read_b128 v[148:151], v241 offset:52224
	ds_read_b128 v[168:171], v241 offset:53248
	ds_read_b128 v[172:175], v241 offset:54272
	ds_read_b128 v[176:179], v241 offset:55296
	ds_read_b128 v[180:183], v241 offset:56320
	global_load_lds_dwordx4 v192, s[8:9] offset:128
	s_add_i32 m0, s2, 0x1f80
	s_add_u32 s2, s8, 0x40080
	global_load_lds_dwordx4 v202, s[8:9] offset:128
	s_addc_u32 s3, s9, 0
	s_add_i32 s8, s31, s18
	s_mov_b32 m0, s8
	s_nop 0
	global_load_lds_dwordx4 v192, s[2:3]
	s_add_i32 m0, s8, 0x2000
	s_nop 0
	global_load_lds_dwordx4 v202, s[2:3]
	s_add_i32 m0, s21, 0xffffff80
	s_nop 0
	global_load_lds_dwordx4 v198, s[10:11] offset:128
	s_add_i32 m0, s62, 0xffffff80
	s_nop 0
	global_load_lds_dwordx4 v200, s[10:11] offset:128
	s_waitcnt vmcnt(8)
	s_waitcnt lgkmcnt(0)
	s_barrier
	s_setprio 1
	s_waitcnt lgkmcnt(0)
	v_mfma_f32_16x16x32_bf16 v[60:63], v[72:75], v[136:139], v[60:63]
	v_mfma_f32_16x16x32_bf16 v[56:59], v[80:83], v[136:139], v[56:59]
	v_mfma_f32_16x16x32_bf16 v[44:47], v[72:75], v[144:147], v[44:47]
	v_mfma_f32_16x16x32_bf16 v[40:43], v[80:83], v[144:147], v[40:43]
	v_mfma_f32_16x16x32_bf16 v[28:31], v[72:75], v[168:171], v[28:31]
	v_mfma_f32_16x16x32_bf16 v[24:27], v[80:83], v[168:171], v[24:27]
	v_mfma_f32_16x16x32_bf16 v[12:15], v[72:75], v[176:179], v[12:15]
	v_mfma_f32_16x16x32_bf16 v[8:11], v[80:83], v[176:179], v[8:11]
	v_mfma_f32_16x16x32_bf16 v[60:63], v[76:79], v[140:143], v[60:63]
	v_mfma_f32_16x16x32_bf16 v[56:59], v[84:87], v[140:143], v[56:59]
	v_mfma_f32_16x16x32_bf16 v[44:47], v[76:79], v[148:151], v[44:47]
	v_mfma_f32_16x16x32_bf16 v[40:43], v[84:87], v[148:151], v[40:43]
	v_mfma_f32_16x16x32_bf16 v[28:31], v[76:79], v[172:175], v[28:31]
	v_mfma_f32_16x16x32_bf16 v[24:27], v[84:87], v[172:175], v[24:27]
	v_mfma_f32_16x16x32_bf16 v[12:15], v[76:79], v[180:183], v[12:15]
	v_mfma_f32_16x16x32_bf16 v[8:11], v[84:87], v[180:183], v[8:11]
	s_setprio 0
	s_setprio 1
	v_mfma_f32_16x16x32_bf16 v[52:55], v[104:107], v[136:139], v[52:55]
	v_mfma_f32_16x16x32_bf16 v[48:51], v[112:115], v[136:139], v[48:51]
	v_mfma_f32_16x16x32_bf16 v[36:39], v[104:107], v[144:147], v[36:39]
	v_mfma_f32_16x16x32_bf16 v[32:35], v[112:115], v[144:147], v[32:35]
	v_mfma_f32_16x16x32_bf16 v[20:23], v[104:107], v[168:171], v[20:23]
	v_mfma_f32_16x16x32_bf16 v[16:19], v[112:115], v[168:171], v[16:19]
	v_mfma_f32_16x16x32_bf16 v[4:7], v[104:107], v[176:179], v[4:7]
	v_mfma_f32_16x16x32_bf16 v[0:3], v[112:115], v[176:179], v[0:3]
	v_mfma_f32_16x16x32_bf16 v[52:55], v[108:111], v[140:143], v[52:55]
	v_mfma_f32_16x16x32_bf16 v[48:51], v[116:119], v[140:143], v[48:51]
	v_mfma_f32_16x16x32_bf16 v[36:39], v[108:111], v[148:151], v[36:39]
	v_mfma_f32_16x16x32_bf16 v[32:35], v[116:119], v[148:151], v[32:35]
	v_mfma_f32_16x16x32_bf16 v[20:23], v[108:111], v[172:175], v[20:23]
	v_mfma_f32_16x16x32_bf16 v[16:19], v[116:119], v[172:175], v[16:19]
	v_mfma_f32_16x16x32_bf16 v[4:7], v[108:111], v[180:183], v[4:7]
	v_mfma_f32_16x16x32_bf16 v[0:3], v[116:119], v[180:183], v[0:3]
	s_setprio 0
	s_barrier
	s_add_i32 s78, s78, 2
	s_add_u32 s16, s16, 0x100
	s_addc_u32 s17, s17, 0
	s_add_u32 s0, s0, 0x100
	s_addc_u32 s1, s1, 0
	s_cmp_gt_u32 s78, 13
	s_cbranch_scc0 .LBB0_817
	s_and_b64 vcc, exec, s[66:67]
	s_cbranch_vccz .LBB0_820
	s_barrier
